# nt hints extended to ma_ret V loads and mc_item<0/1> gate loads / Y stores
# baseline (speedup 1.0000x reference)
; __device__ __forceinline__ int otid() { int t = threadIdx.x; asm volatile("" : "+v"(t)); return t; }
; __device__ __forceinline__ void ma_ret_item(const Params& p, ldsp lds, int item) {
;     const int tid = otid(), lane = tid & 63, wave = __builtin_amdgcn_readfirstlane(tid >> 6), l15 = lane & 15, q4 = lane >> 4;
;     const int es = item & 3, sc = (item >> 2) & 7, bh = item >> 5, b = bh >> 2, h = bh & 3;
;     ldsp KTt = lds; ldsp VTt = lds + 36864;
;     const bf16_t* Pb = (const bf16_t*)(p.ws + WS_P);
;     f32x4 acc[16];
; #pragma unroll
;     for (int i = 0; i < 16; ++i) acc[i] = (f32x4){0.f, 0.f, 0.f, 0.f};
;     u32x4 kr[4], vr[2];
;     { const size_t rowq = (size_t)b * 2048 + (sc * 4) * 64;
;       ld_T<256>(kr, Pb + rowq * NO + O_K + h * 256, NO, wave, lane); ld_T<128>(vr, Pb + rowq * NO + O_V + h * 512 + es * 128, NO, wave, lane); }
.LBB0_677:
	s_lshl_b32 s0, s12, 6
	v_readlane_b32 s1, v253, 36
	s_add_i32 s0, s1, s0
	s_ashr_i32 s10, s0, 5
	s_ashr_i32 s11, s10, 31
	s_lshl_b64 s[8:9], s[10:11], 11
	v_readlane_b32 s11, v253, 37
	v_mov_b32_e32 v2, v161
	s_or_b32 s8, s8, s11
	s_ashr_i32 s0, s0, 3
	v_readfirstlane_b32 s1, v2
	s_mulk_i32 s9, 0x3000
	s_mul_hi_u32 s11, s8, 0x3000
	s_ashr_i32 s1, s1, 6
	s_and_b32 s13, s0, 3
	s_add_i32 s11, s11, s9
	s_mulk_i32 s8, 0x3000
	s_add_u32 s14, s26, s8
	s_addc_u32 s11, s27, s11
	s_lshl_b32 s15, s13, 9
	s_add_u32 s8, s14, s15
	s_addc_u32 s9, s11, 0
	s_lshl_b32 s16, s1, 5
	v_and_b32_e32 v0, 31, v2
	v_and_or_b32 v29, s16, 32, v0
	v_mul_u32_u24_e32 v0, 0x1800, v29
	v_lshlrev_b32_e32 v16, 1, v0
	v_lshl_add_u64 v[0:1], s[8:9], 0, v[16:17]
	s_and_b32 s8, s1, 0x1ffffffe
	v_bfe_u32 v30, v2, 5, 1
	v_and_b32_e32 v95, 15, v2
	v_bfe_u32 v28, v2, 4, 2
	v_or_b32_e32 v2, s8, v30
	s_lshl_b32 s13, s13, 10
	v_lshlrev_b32_e32 v2, 3, v2
	s_add_u32 s8, s14, s13
	v_ashrrev_i32_e32 v3, 31, v2
	s_addc_u32 s9, s11, 0
	v_readlane_b32 s11, v255, 11
	v_lshlrev_b64 v[26:27], 1, v[2:3]
	s_add_u32 s8, s8, s11
	v_lshl_add_u64 v[0:1], v[0:1], 0, v[26:27]
	s_addc_u32 s9, s9, 0
	global_load_dwordx4 v[22:25], v[0:1], off offset:2048
	global_load_dwordx4 v[18:21], v[0:1], off offset:2176
	global_load_dwordx4 v[12:15], v[0:1], off offset:2304
	global_load_dwordx4 v[4:7], v[0:1], off offset:2432
	v_lshl_add_u64 v[0:1], s[8:9], 0, v[16:17]
	v_lshl_add_u64 v[0:1], v[0:1], 0, v[26:27]
	s_mov_b64 s[8:9], 0x1000
	v_lshl_add_u64 v[2:3], v[0:1], 0, s[8:9]
	v_add_co_u32_e32 v0, vcc, s57, v0
	s_and_b32 s8, s1, 0x3fffffe
	s_nop 0
	v_addc_co_u32_e32 v1, vcc, 0, v1, vcc
	global_load_dwordx4 v[8:11], v[0:1], off nt
	s_nop 0
	global_load_dwordx4 v[0:3], v[2:3], off offset:128 nt
	v_or_b32_e32 v30, s8, v30
	s_movk_i32 s8, 0x240
	v_mul_lo_u32 v30, v30, s8
	v_or_b32_e32 v29, v29, v30
	s_lshl_b32 s8, s1, 4
	v_lshl_add_u32 v100, v29, 1, 0
	v_or_b32_e32 v29, s8, v95
	v_lshlrev_b32_e32 v94, 3, v28
	v_mul_lo_u32 v29, v29, s53
	v_or_b32_e32 v28, 32, v94
	v_mul_u32_u24_e32 v30, 0x48, v95
	v_add_lshl_u32 v31, v28, v30, 1
	v_add_lshl_u32 v32, v29, v94, 1
	v_add_lshl_u32 v33, v94, v30, 1
	v_mov_b32_e32 v29, 0x480
	v_mov_b32_e32 v30, 0x900
	v_mov_b32_e32 v36, 0xd80
	v_mov_b32_e32 v38, 0x1200
	v_mov_b32_e32 v40, 0x1680
	v_mov_b32_e32 v42, 0x1b00
	v_mov_b32_e32 v44, 0x1f80
	v_mov_b32_e32 v46, 0x2400
	v_mov_b32_e32 v48, 0x2880
	v_mov_b32_e32 v50, 0x2d00
	v_mov_b32_e32 v52, 0x3180
	v_mov_b32_e32 v54, 0x3600
	v_mov_b32_e32 v56, 0x3a80
	v_mov_b32_e32 v58, 0x3f00
	v_mov_b32_e32 v60, 0x4380
	s_mul_i32 s1, s10, 0x1800000
	v_mad_u32_u24 v29, v95, s53, v29
	v_mad_u32_u24 v30, v95, s53, v30
	v_mad_u32_u24 v36, v95, s53, v36
	v_mad_u32_u24 v38, v95, s53, v38
	v_mad_u32_u24 v40, v95, s53, v40
	v_mad_u32_u24 v42, v95, s53, v42
	v_mad_u32_u24 v44, v95, s53, v44
	v_mad_u32_u24 v46, v95, s53, v46
	v_mad_u32_u24 v48, v95, s53, v48
	v_mad_u32_u24 v50, v95, s53, v50
	v_mad_u32_u24 v52, v95, s53, v52
	v_mad_u32_u24 v54, v95, s53, v54
	v_mad_u32_u24 v56, v95, s53, v56
	v_mad_u32_u24 v58, v95, s53, v58
	v_mad_u32_u24 v60, v95, s53, v60
	s_mul_hi_i32 s11, s10, 0x1800000
	s_or_b32 s10, s1, s13
	v_add_lshl_u32 v34, v94, v29, 1
	v_add_lshl_u32 v37, v94, v36, 1
	v_add_lshl_u32 v39, v94, v38, 1
	v_add_lshl_u32 v41, v94, v40, 1
	v_add_lshl_u32 v43, v94, v42, 1
	v_add_lshl_u32 v45, v94, v44, 1
	v_add_lshl_u32 v47, v94, v46, 1
	v_add_lshl_u32 v49, v94, v48, 1
	v_add_lshl_u32 v51, v94, v50, 1
	v_add_lshl_u32 v53, v94, v52, 1
	v_add_lshl_u32 v55, v94, v54, 1
	v_add_lshl_u32 v57, v94, v56, 1
	v_add_lshl_u32 v59, v94, v58, 1
	v_add_lshl_u32 v61, v94, v60, 1
	v_add_lshl_u32 v62, v28, v29, 1
	v_add_lshl_u32 v63, v28, v30, 1
	v_add_lshl_u32 v36, v28, v36, 1
	v_add_lshl_u32 v38, v28, v38, 1
	v_add_lshl_u32 v40, v28, v40, 1
	v_add_lshl_u32 v42, v28, v42, 1
	v_add_lshl_u32 v44, v28, v44, 1
	v_add_lshl_u32 v46, v28, v46, 1
	v_add_lshl_u32 v48, v28, v48, 1
	v_add_lshl_u32 v50, v28, v50, 1
	v_add_lshl_u32 v52, v28, v52, 1
	v_add_lshl_u32 v54, v28, v54, 1
	v_add_lshl_u32 v56, v28, v56, 1
	v_add_lshl_u32 v58, v28, v58, 1
	v_add_lshl_u32 v60, v28, v60, 1
	v_lshl_add_u64 v[28:29], s[10:11], 0, v[26:27]
	s_or_b32 s10, s1, s15
	v_readlane_b32 s16, v254, 51
	v_lshl_add_u64 v[26:27], s[10:11], 0, v[26:27]
	v_readlane_b32 s10, v254, 53
	v_add_lshl_u32 v35, v94, v30, 1
	v_lshl_add_u64 v[28:29], v[28:29], 0, v[16:17]
	v_readlane_b32 s17, v254, 52
	v_lshl_add_u64 v[26:27], v[26:27], 0, v[16:17]
	v_readlane_b32 s11, v254, 54
	v_mov_b32_e32 v30, 0
	v_lshl_add_u64 v[96:97], s[16:17], 0, v[28:29]
	v_lshl_add_u64 v[98:99], s[10:11], 0, v[26:27]
	s_mov_b64 s[10:11], 0
	v_add_u32_e32 v130, 0, v32
	v_add_u32_e32 v132, 0, v33
	v_add_u32_e32 v131, 0, v34
	v_add_u32_e32 v129, 0, v35
	v_add_u32_e32 v128, 0, v37
	v_add_u32_e32 v127, 0, v39
	v_add_u32_e32 v126, 0, v41
	v_add_u32_e32 v125, 0, v43
	v_add_u32_e32 v124, 0, v45
	v_add_u32_e32 v123, 0, v47
	v_add_u32_e32 v122, 0, v49
	v_add_u32_e32 v121, 0, v51
	v_add_u32_e32 v120, 0, v53
	v_add_u32_e32 v119, 0, v55
	v_add_u32_e32 v118, 0, v57
	v_add_u32_e32 v117, 0, v59
	v_add_u32_e32 v116, 0, v61
	v_add_u32_e32 v115, 0, v31
	v_add_u32_e32 v114, 0, v62
	v_add_u32_e32 v113, 0, v63
	v_add_u32_e32 v112, 0, v36
	v_add_u32_e32 v111, 0, v38
	v_add_u32_e32 v110, 0, v40
	v_add_u32_e32 v109, 0, v42
	v_add_u32_e32 v108, 0, v44
	v_add_u32_e32 v107, 0, v46
	v_add_u32_e32 v106, 0, v48
	v_add_u32_e32 v105, 0, v50
	v_add_u32_e32 v104, 0, v52
	v_add_u32_e32 v103, 0, v54
	v_add_u32_e32 v102, 0, v56
	v_add_u32_e32 v101, 0, v58
	v_add_u32_e32 v16, 0, v60
	v_mov_b32_e32 v31, v30
	v_mov_b32_e32 v32, v30
	v_mov_b32_e32 v33, v30
	v_mov_b32_e32 v86, v30
; __device__ __forceinline__ f32x4 mma16(bf16x8 a, bf16x8 b, f32x4 c) { return __builtin_amdgcn_mfma_f32_16x16x32_bf16(a, b, c, 0, 0, 0); }
; __device__ __forceinline__ void ma_ret_item(const Params& p, ldsp lds, int item) {
;     ...
; #pragma unroll
;     for (int i = 0; i < 16; ++i) acc[i] = (f32x4){0.f, 0.f, 0.f, 0.f};
;     u32x4 kr[4], vr[2];
;     { const size_t rowq = (size_t)b * 2048 + (sc * 4) * 64;
;       ld_T<256>(kr, Pb + rowq * NO + O_K + h * 256, NO, wave, lane); ld_T<128>(vr, Pb + rowq * NO + O_V + h * 512 + es * 128, NO, wave, lane); }
;     for (int j = 0; j < 4; ++j) { const size_t rowj = (size_t)b * 2048 + (sc * 4 + j) * 64;
;         st_T<256>(KTt, 72, kr, wave, lane); st_T<128>(VTt, 72, vr, wave, lane);
;         __syncthreads();
;         if (j < 3) { const size_t rown = rowj + 64; ld_T<256>(kr, Pb + rown * NO + O_K + h * 256, NO, wave, lane); ld_T<128>(vr, Pb + rown * NO + O_V + h * 512 + es * 128, NO, wave, lane); }
; #pragma unroll
;         for (int ks = 0; ks < 2; ++ks) { const bf16x8 bf = ldfrag(VTt, (16 * wave + l15) * 72 + 32 * ks + 8 * q4);
; #pragma unroll
;             for (int i = 0; i < 16; ++i) acc[i] = mma16(ldfrag(KTt, (16 * i + l15) * 72 + 32 * ks + 8 * q4), bf, acc[i]); }
	v_mov_b32_e32 v87, v30
	v_mov_b32_e32 v88, v30
	v_mov_b32_e32 v89, v30
	v_mov_b32_e32 v82, v30
	v_mov_b32_e32 v83, v30
	v_mov_b32_e32 v84, v30
	v_mov_b32_e32 v85, v30
	v_mov_b32_e32 v78, v30
	v_mov_b32_e32 v79, v30
	v_mov_b32_e32 v80, v30
	v_mov_b32_e32 v81, v30
	v_mov_b32_e32 v74, v30
	v_mov_b32_e32 v75, v30
	v_mov_b32_e32 v76, v30
	v_mov_b32_e32 v77, v30
	v_mov_b32_e32 v70, v30
	v_mov_b32_e32 v71, v30
	v_mov_b32_e32 v72, v30
	v_mov_b32_e32 v73, v30
	v_mov_b32_e32 v66, v30
	v_mov_b32_e32 v67, v30
	v_mov_b32_e32 v68, v30
	v_mov_b32_e32 v69, v30
	v_mov_b32_e32 v62, v30
	v_mov_b32_e32 v63, v30
	v_mov_b32_e32 v64, v30
	v_mov_b32_e32 v65, v30
	v_mov_b32_e32 v58, v30
	v_mov_b32_e32 v59, v30
	v_mov_b32_e32 v60, v30
	v_mov_b32_e32 v61, v30
	v_mov_b32_e32 v54, v30
	v_mov_b32_e32 v55, v30
	v_mov_b32_e32 v56, v30
	v_mov_b32_e32 v57, v30
	v_mov_b32_e32 v50, v30
	v_mov_b32_e32 v51, v30
	v_mov_b32_e32 v52, v30
	v_mov_b32_e32 v53, v30
	v_mov_b32_e32 v46, v30
	v_mov_b32_e32 v47, v30
	v_mov_b32_e32 v48, v30
	v_mov_b32_e32 v49, v30
	v_mov_b32_e32 v42, v30
	v_mov_b32_e32 v43, v30
	v_mov_b32_e32 v44, v30
	v_mov_b32_e32 v45, v30
	v_mov_b32_e32 v38, v30
	v_mov_b32_e32 v39, v30
	v_mov_b32_e32 v40, v30
	v_mov_b32_e32 v41, v30
	v_mov_b32_e32 v34, v30
	v_mov_b32_e32 v35, v30
	v_mov_b32_e32 v36, v30
	v_mov_b32_e32 v37, v30
	v_mov_b32_e32 v26, v30
	v_mov_b32_e32 v27, v30
	v_mov_b32_e32 v28, v30
	v_mov_b32_e32 v29, v30
.LBB0_678:
	s_waitcnt vmcnt(5)
	ds_write_b16 v100, v22
	ds_write_b16_d16_hi v100, v22 offset:144
	ds_write_b16 v100, v23 offset:288
	ds_write_b16_d16_hi v100, v23 offset:432
	ds_write_b16 v100, v24 offset:576
	ds_write_b16_d16_hi v100, v24 offset:720
	ds_write_b16 v100, v25 offset:864
	ds_write_b16_d16_hi v100, v25 offset:1008
	s_waitcnt vmcnt(4)
	ds_write_b16 v100, v18 offset:9216
	ds_write_b16_d16_hi v100, v18 offset:9360
	ds_write_b16 v100, v19 offset:9504
	ds_write_b16_d16_hi v100, v19 offset:9648
	ds_write_b16 v100, v20 offset:9792
	ds_write_b16_d16_hi v100, v20 offset:9936
	ds_write_b16 v100, v21 offset:10080
	ds_write_b16_d16_hi v100, v21 offset:10224
	s_waitcnt vmcnt(3)
	ds_write_b16 v100, v12 offset:18432
	ds_write_b16_d16_hi v100, v12 offset:18576
	ds_write_b16 v100, v13 offset:18720
	ds_write_b16_d16_hi v100, v13 offset:18864
	ds_write_b16 v100, v14 offset:19008
	ds_write_b16_d16_hi v100, v14 offset:19152
	ds_write_b16 v100, v15 offset:19296
	ds_write_b16_d16_hi v100, v15 offset:19440
	s_waitcnt vmcnt(2)
	ds_write_b16 v100, v4 offset:27648
	ds_write_b16_d16_hi v100, v4 offset:27792
	ds_write_b16 v100, v5 offset:27936
	ds_write_b16_d16_hi v100, v5 offset:28080
	ds_write_b16 v100, v6 offset:28224
	ds_write_b16_d16_hi v100, v6 offset:28368
	ds_write_b16 v100, v7 offset:28512
	ds_write_b16_d16_hi v100, v7 offset:28656
	s_waitcnt vmcnt(1)
	ds_write_b16 v100, v8 offset:36864
	ds_write_b16_d16_hi v100, v8 offset:37008
	ds_write_b16 v100, v9 offset:37152
	ds_write_b16_d16_hi v100, v9 offset:37296
	ds_write_b16 v100, v10 offset:37440
	ds_write_b16_d16_hi v100, v10 offset:37584
	ds_write_b16 v100, v11 offset:37728
	ds_write_b16_d16_hi v100, v11 offset:37872
	s_waitcnt vmcnt(0)
	ds_write_b16 v100, v0 offset:46080
	ds_write_b16_d16_hi v100, v0 offset:46224
	ds_write_b16 v100, v1 offset:46368
	ds_write_b16_d16_hi v100, v1 offset:46512
	ds_write_b16 v100, v2 offset:46656
	ds_write_b16_d16_hi v100, v2 offset:46800
	ds_write_b16 v100, v3 offset:46944
	ds_write_b16_d16_hi v100, v3 offset:47088
	v_lshl_add_u64 v[0:1], v[98:99], 0, s[10:11]
	s_waitcnt lgkmcnt(0)
	s_barrier
	global_load_dwordx4 v[22:25], v[0:1], off offset:-256
	global_load_dwordx4 v[18:21], v[0:1], off offset:-128
	global_load_dwordx4 v[12:15], v[0:1], off
	global_load_dwordx4 v[4:7], v[0:1], off offset:128
	v_lshl_add_u64 v[0:1], v[96:97], 0, s[10:11]
	v_add_co_u32_e32 v0, vcc, s54, v0
	s_add_u32 s10, s10, 0xc0000
	s_nop 0
	v_addc_co_u32_e32 v1, vcc, 0, v1, vcc
	global_load_dwordx4 v[8:11], v[0:1], off nt
	s_nop 0
	global_load_dwordx4 v[0:3], v[0:1], off offset:128 nt
	ds_read_b128 v[90:93], v130 offset:36864
	ds_read_b128 v[242:245], v130 offset:36928
	ds_read_b128 v[210:213], v132
	ds_read_b128 v[214:217], v131
	ds_read_b128 v[218:221], v129
	ds_read_b128 v[222:225], v128
	ds_read_b128 v[226:229], v127
	ds_read_b128 v[230:233], v126
	ds_read_b128 v[234:237], v125
	ds_read_b128 v[238:241], v124
	s_addc_u32 s11, s11, 0
	s_cmp_lg_u32 s10, 0x240000
	s_waitcnt lgkmcnt(7)
	v_mfma_f32_16x16x32_bf16 v[26:29], v[210:213], v[90:93], v[26:29]
	ds_read_b128 v[210:213], v123
	s_waitcnt lgkmcnt(7)
	v_mfma_f32_16x16x32_bf16 v[34:37], v[214:217], v[90:93], v[34:37]
	ds_read_b128 v[214:217], v122
	s_waitcnt lgkmcnt(7)
	v_mfma_f32_16x16x32_bf16 v[38:41], v[218:221], v[90:93], v[38:41]
	ds_read_b128 v[218:221], v121
	s_waitcnt lgkmcnt(7)
	v_mfma_f32_16x16x32_bf16 v[42:45], v[222:225], v[90:93], v[42:45]
	ds_read_b128 v[222:225], v120
	s_waitcnt lgkmcnt(7)
	v_mfma_f32_16x16x32_bf16 v[46:49], v[226:229], v[90:93], v[46:49]
	ds_read_b128 v[226:229], v119
	s_waitcnt lgkmcnt(7)
	v_mfma_f32_16x16x32_bf16 v[50:53], v[230:233], v[90:93], v[50:53]
	ds_read_b128 v[230:233], v118
	s_waitcnt lgkmcnt(7)
	v_mfma_f32_16x16x32_bf16 v[54:57], v[234:237], v[90:93], v[54:57]
	ds_read_b128 v[234:237], v117
	s_waitcnt lgkmcnt(7)
	v_mfma_f32_16x16x32_bf16 v[58:61], v[238:241], v[90:93], v[58:61]
	ds_read_b128 v[238:241], v116
	s_waitcnt lgkmcnt(7)
	v_mfma_f32_16x16x32_bf16 v[62:65], v[210:213], v[90:93], v[62:65]
	ds_read_b128 v[210:213], v115
	s_waitcnt lgkmcnt(7)
	v_mfma_f32_16x16x32_bf16 v[66:69], v[214:217], v[90:93], v[66:69]
	ds_read_b128 v[214:217], v114
	s_waitcnt lgkmcnt(7)
; __device__ __forceinline__ f32x4 mma16(bf16x8 a, bf16x8 b, f32x4 c) { return __builtin_amdgcn_mfma_f32_16x16x32_bf16(a, b, c, 0, 0, 0); }
; __device__ __forceinline__ void ma_ret_item(const Params& p, ldsp lds, int item) {
;     ...
;     for (int j = 0; j < 4; ++j) { const size_t rowj = (size_t)b * 2048 + (sc * 4 + j) * 64;
;         st_T<256>(KTt, 72, kr, wave, lane); st_T<128>(VTt, 72, vr, wave, lane);
;         __syncthreads();
;         if (j < 3) { const size_t rown = rowj + 64; ld_T<256>(kr, Pb + rown * NO + O_K + h * 256, NO, wave, lane); ld_T<128>(vr, Pb + rown * NO + O_V + h * 512 + es * 128, NO, wave, lane); }
; #pragma unroll
;         for (int ks = 0; ks < 2; ++ks) { const bf16x8 bf = ldfrag(VTt, (16 * wave + l15) * 72 + 32 * ks + 8 * q4);
; #pragma unroll
;             for (int i = 0; i < 16; ++i) acc[i] = mma16(ldfrag(KTt, (16 * i + l15) * 72 + 32 * ks + 8 * q4), bf, acc[i]); }
;         __syncthreads(); }
	v_mfma_f32_16x16x32_bf16 v[70:73], v[218:221], v[90:93], v[70:73]
	ds_read_b128 v[218:221], v113
	s_waitcnt lgkmcnt(7)
	v_mfma_f32_16x16x32_bf16 v[74:77], v[222:225], v[90:93], v[74:77]
	ds_read_b128 v[222:225], v112
	s_waitcnt lgkmcnt(7)
	v_mfma_f32_16x16x32_bf16 v[78:81], v[226:229], v[90:93], v[78:81]
	ds_read_b128 v[226:229], v111
	s_waitcnt lgkmcnt(7)
	v_mfma_f32_16x16x32_bf16 v[82:85], v[230:233], v[90:93], v[82:85]
	ds_read_b128 v[230:233], v110
	s_waitcnt lgkmcnt(7)
	v_mfma_f32_16x16x32_bf16 v[86:89], v[234:237], v[90:93], v[86:89]
	ds_read_b128 v[234:237], v109
	s_waitcnt lgkmcnt(7)
	v_mfma_f32_16x16x32_bf16 v[30:33], v[238:241], v[90:93], v[30:33]
	ds_read_b128 v[238:241], v108
	s_waitcnt lgkmcnt(7)
	v_mfma_f32_16x16x32_bf16 v[26:29], v[210:213], v[242:245], v[26:29]
	ds_read_b128 v[210:213], v107
	s_waitcnt lgkmcnt(7)
	v_mfma_f32_16x16x32_bf16 v[34:37], v[214:217], v[242:245], v[34:37]
	ds_read_b128 v[214:217], v106
	s_waitcnt lgkmcnt(7)
	v_mfma_f32_16x16x32_bf16 v[38:41], v[218:221], v[242:245], v[38:41]
	ds_read_b128 v[218:221], v105
	s_waitcnt lgkmcnt(7)
	v_mfma_f32_16x16x32_bf16 v[42:45], v[222:225], v[242:245], v[42:45]
	ds_read_b128 v[222:225], v104
	s_waitcnt lgkmcnt(7)
	v_mfma_f32_16x16x32_bf16 v[46:49], v[226:229], v[242:245], v[46:49]
	ds_read_b128 v[226:229], v103
	s_waitcnt lgkmcnt(7)
	v_mfma_f32_16x16x32_bf16 v[50:53], v[230:233], v[242:245], v[50:53]
	ds_read_b128 v[230:233], v102
	s_waitcnt lgkmcnt(7)
	v_mfma_f32_16x16x32_bf16 v[54:57], v[234:237], v[242:245], v[54:57]
	ds_read_b128 v[234:237], v101
	s_waitcnt lgkmcnt(7)
	v_mfma_f32_16x16x32_bf16 v[58:61], v[238:241], v[242:245], v[58:61]
	ds_read_b128 v[238:241], v16
	s_waitcnt lgkmcnt(7)
	v_mfma_f32_16x16x32_bf16 v[62:65], v[210:213], v[242:245], v[62:65]
	s_waitcnt lgkmcnt(6)
	v_mfma_f32_16x16x32_bf16 v[66:69], v[214:217], v[242:245], v[66:69]
	s_waitcnt lgkmcnt(5)
	v_mfma_f32_16x16x32_bf16 v[70:73], v[218:221], v[242:245], v[70:73]
	s_waitcnt lgkmcnt(4)
	v_mfma_f32_16x16x32_bf16 v[74:77], v[222:225], v[242:245], v[74:77]
	s_waitcnt lgkmcnt(3)
	v_mfma_f32_16x16x32_bf16 v[78:81], v[226:229], v[242:245], v[78:81]
	s_waitcnt lgkmcnt(2)
	v_mfma_f32_16x16x32_bf16 v[82:85], v[230:233], v[242:245], v[82:85]
	s_waitcnt lgkmcnt(1)
	v_mfma_f32_16x16x32_bf16 v[86:89], v[234:237], v[242:245], v[86:89]
	s_waitcnt lgkmcnt(0)
	s_barrier
	v_mfma_f32_16x16x32_bf16 v[30:33], v[238:241], v[242:245], v[30:33]
	s_cbranch_scc1 .LBB0_678
	s_waitcnt vmcnt(5)
	ds_write_b16 v100, v22
	ds_write_b16_d16_hi v100, v22 offset:144
	ds_write_b16 v100, v23 offset:288
	ds_write_b16_d16_hi v100, v23 offset:432
	ds_write_b16 v100, v24 offset:576
	ds_write_b16_d16_hi v100, v24 offset:720
	ds_write_b16 v100, v25 offset:864
	ds_write_b16_d16_hi v100, v25 offset:1008
	s_waitcnt vmcnt(4)
	ds_write_b16 v100, v18 offset:9216
	ds_write_b16_d16_hi v100, v18 offset:9360
	ds_write_b16 v100, v19 offset:9504
	ds_write_b16_d16_hi v100, v19 offset:9648
	ds_write_b16 v100, v20 offset:9792
	ds_write_b16_d16_hi v100, v20 offset:9936
	ds_write_b16 v100, v21 offset:10080
	ds_write_b16_d16_hi v100, v21 offset:10224
	s_waitcnt vmcnt(3)
	ds_write_b16 v100, v12 offset:18432
	ds_write_b16_d16_hi v100, v12 offset:18576
	ds_write_b16 v100, v13 offset:18720
	ds_write_b16_d16_hi v100, v13 offset:18864
	ds_write_b16 v100, v14 offset:19008
	ds_write_b16_d16_hi v100, v14 offset:19152
	ds_write_b16 v100, v15 offset:19296
	ds_write_b16_d16_hi v100, v15 offset:19440
	s_waitcnt vmcnt(2)
	ds_write_b16 v100, v4 offset:27648
	ds_write_b16_d16_hi v100, v4 offset:27792
	ds_write_b16 v100, v5 offset:27936
	ds_write_b16_d16_hi v100, v5 offset:28080
	ds_write_b16 v100, v6 offset:28224
	ds_write_b16_d16_hi v100, v6 offset:28368
	ds_write_b16 v100, v7 offset:28512
	ds_write_b16_d16_hi v100, v7 offset:28656
	s_waitcnt vmcnt(1)
	ds_write_b16 v100, v8 offset:36864
	ds_write_b16_d16_hi v100, v8 offset:37008
	ds_write_b16 v100, v9 offset:37152
	ds_write_b16_d16_hi v100, v9 offset:37296
	ds_write_b16 v100, v10 offset:37440
	ds_write_b16_d16_hi v100, v10 offset:37584
	ds_write_b16 v100, v11 offset:37728
	ds_write_b16_d16_hi v100, v11 offset:37872
	s_waitcnt vmcnt(0)
	ds_write_b16 v100, v0 offset:46080
	ds_write_b16_d16_hi v100, v0 offset:46224
	ds_write_b16 v100, v1 offset:46368
	ds_write_b16_d16_hi v100, v1 offset:46512
	ds_write_b16 v100, v2 offset:46656
	ds_write_b16_d16_hi v100, v2 offset:46800
	ds_write_b16 v100, v3 offset:46944
	ds_write_b16_d16_hi v100, v3 offset:47088
	s_waitcnt lgkmcnt(0)
	s_barrier
; __device__ __forceinline__ unsigned pk2(float lo, float hi) { return pg8::cvt_pk_bf16(lo, hi); }
; __device__ __forceinline__ f32x4 mma16(bf16x8 a, bf16x8 b, f32x4 c) { return __builtin_amdgcn_mfma_f32_16x16x32_bf16(a, b, c, 0, 0, 0); }
; __device__ __forceinline__ void ma_ret_item(const Params& p, ldsp lds, int item) {
;     ...
;         for (int ks = 0; ks < 2; ++ks) { const bf16x8 bf = ldfrag(VTt, (16 * wave + l15) * 72 + 32 * ks + 8 * q4);
; #pragma unroll
;             for (int i = 0; i < 16; ++i) acc[i] = mma16(ldfrag(KTt, (16 * i + l15) * 72 + 32 * ks + 8 * q4), bf, acc[i]); }
;         __syncthreads(); }
;     bf16_t* HL = (bf16_t*)(p.ws + WS_HL) + (((size_t)bh * 8 + sc) * 512 + es * 128 + 16 * wave + l15) * 256;
; #pragma unroll
;     for (int i = 0; i < 16; ++i) { u32x2 w; w.x = pk2(acc[i][0], acc[i][1]); w.y = pk2(acc[i][2], acc[i][3]); *(u32x2*)(HL + 16 * i + 4 * q4) = w; }
	ds_read_b128 v[0:3], v132
	ds_read_b128 v[4:7], v130 offset:36864
	ds_read_b128 v[8:11], v131
	ds_read_b128 v[12:15], v130 offset:36928
	ds_read_b128 v[18:21], v129
	ds_read_b128 v[22:25], v128
	s_waitcnt lgkmcnt(4)
	v_mfma_f32_16x16x32_bf16 v[0:3], v[0:3], v[4:7], v[26:29]
	s_ashr_i32 s1, s0, 31
	v_readlane_b32 s10, v255, 9
	s_lshl_b64 s[0:1], s[0:1], 12
	s_waitcnt lgkmcnt(3)
	v_mfma_f32_16x16x32_bf16 v[8:11], v[8:11], v[4:7], v[34:37]
	ds_read_b128 v[26:29], v127
	v_readlane_b32 s11, v255, 10
	s_or_b64 s[0:1], s[0:1], s[10:11]
	s_waitcnt lgkmcnt(2)
	v_mfma_f32_16x16x32_bf16 v[18:21], v[18:21], v[4:7], v[38:41]
	ds_read_b128 v[34:37], v126
	s_ashr_i32 s9, s8, 31
	s_add_i32 s12, s12, 1
	s_waitcnt lgkmcnt(2)
	v_mfma_f32_16x16x32_bf16 v[22:25], v[22:25], v[4:7], v[42:45]
	ds_read_b128 v[38:41], v125
	s_cmp_eq_u32 s12, 4
	s_nop 0
	ds_read_b128 v[42:45], v124
	s_waitcnt lgkmcnt(3)
	v_mfma_f32_16x16x32_bf16 v[26:29], v[26:29], v[4:7], v[46:49]
	s_waitcnt lgkmcnt(2)
	v_mfma_f32_16x16x32_bf16 v[34:37], v[34:37], v[4:7], v[50:53]
	s_nop 0
	ds_read_b128 v[46:49], v123
	s_nop 0
	ds_read_b128 v[50:53], v122
	s_waitcnt lgkmcnt(3)
	v_mfma_f32_16x16x32_bf16 v[38:41], v[38:41], v[4:7], v[54:57]
	s_waitcnt lgkmcnt(2)
	v_mfma_f32_16x16x32_bf16 v[42:45], v[42:45], v[4:7], v[58:61]
	s_nop 0
	ds_read_b128 v[54:57], v121
	s_nop 0
	ds_read_b128 v[58:61], v120
	s_waitcnt lgkmcnt(3)
	v_mfma_f32_16x16x32_bf16 v[46:49], v[46:49], v[4:7], v[62:65]
	s_waitcnt lgkmcnt(2)
	v_mfma_f32_16x16x32_bf16 v[50:53], v[50:53], v[4:7], v[66:69]
	s_nop 0
	ds_read_b128 v[62:65], v119
	s_nop 0
	ds_read_b128 v[66:69], v118
	s_waitcnt lgkmcnt(3)
	v_mfma_f32_16x16x32_bf16 v[54:57], v[54:57], v[4:7], v[70:73]
	s_waitcnt lgkmcnt(2)
	v_mfma_f32_16x16x32_bf16 v[58:61], v[58:61], v[4:7], v[74:77]
	s_nop 0
	ds_read_b128 v[70:73], v117
	s_nop 0
	ds_read_b128 v[74:77], v116
	s_waitcnt lgkmcnt(3)
	v_mfma_f32_16x16x32_bf16 v[62:65], v[62:65], v[4:7], v[78:81]
	s_waitcnt lgkmcnt(2)
	v_mfma_f32_16x16x32_bf16 v[66:69], v[66:69], v[4:7], v[82:85]
	s_nop 0
	ds_read_b128 v[78:81], v115
	s_waitcnt lgkmcnt(2)
	v_mfma_f32_16x16x32_bf16 v[70:73], v[70:73], v[4:7], v[86:89]
	s_waitcnt lgkmcnt(1)
	v_mfma_f32_16x16x32_bf16 v[4:7], v[74:77], v[4:7], v[30:33]
	ds_read_b128 v[74:77], v113
	s_nop 1
	ds_read_b128 v[30:33], v114
	s_waitcnt lgkmcnt(0)
	v_mfma_f32_16x16x32_bf16 v[8:11], v[30:33], v[12:15], v[8:11]
	ds_read_b128 v[30:33], v112
	v_mfma_f32_16x16x32_bf16 v[18:21], v[74:77], v[12:15], v[18:21]
	ds_read_b128 v[74:77], v111
	s_waitcnt lgkmcnt(1)
	v_mfma_f32_16x16x32_bf16 v[22:25], v[30:33], v[12:15], v[22:25]
	ds_read_b128 v[30:33], v110
	s_waitcnt lgkmcnt(1)
	v_mfma_f32_16x16x32_bf16 v[26:29], v[74:77], v[12:15], v[26:29]
	ds_read_b128 v[74:77], v109
	s_waitcnt lgkmcnt(1)
	v_mfma_f32_16x16x32_bf16 v[30:33], v[30:33], v[12:15], v[34:37]
	s_nop 2
	ds_read_b128 v[34:37], v108
	s_waitcnt lgkmcnt(1)
	v_mfma_f32_16x16x32_bf16 v[38:41], v[74:77], v[12:15], v[38:41]
	ds_read_b128 v[74:77], v107
	s_waitcnt lgkmcnt(1)
	v_mfma_f32_16x16x32_bf16 v[34:37], v[34:37], v[12:15], v[42:45]
	s_nop 2
	ds_read_b128 v[42:45], v106
	s_waitcnt lgkmcnt(1)
	v_mfma_f32_16x16x32_bf16 v[46:49], v[74:77], v[12:15], v[46:49]
	ds_read_b128 v[74:77], v105
	s_waitcnt lgkmcnt(1)
	v_mfma_f32_16x16x32_bf16 v[42:45], v[42:45], v[12:15], v[50:53]
	s_nop 2
	ds_read_b128 v[50:53], v104
	v_mfma_f32_16x16x32_bf16 v[0:3], v[78:81], v[12:15], v[0:3]
	s_waitcnt lgkmcnt(1)
	v_mfma_f32_16x16x32_bf16 v[54:57], v[74:77], v[12:15], v[54:57]
	ds_read_b128 v[74:77], v103
	ds_read_b128 v[78:81], v102
	s_waitcnt lgkmcnt(2)
	v_mfma_f32_16x16x32_bf16 v[50:53], v[50:53], v[12:15], v[58:61]
	s_nop 2
	ds_read_b128 v[58:61], v101
	ds_read_b128 v[82:85], v16
	s_waitcnt lgkmcnt(0)
	s_barrier
	v_mfma_f32_16x16x32_bf16 v[58:61], v[58:61], v[12:15], v[70:73]
	v_cvt_pk_bf16_f32 v0, v0, v1
	v_cvt_pk_bf16_f32 v1, v2, v3
	v_mfma_f32_16x16x32_bf16 v[62:65], v[74:77], v[12:15], v[62:65]
	s_nop 1
	v_or_b32_e32 v70, s0, v95
	v_mov_b32_e32 v71, s1
	v_lshl_add_u64 v[70:71], v[70:71], 0, s[8:9]
	v_readlane_b32 s0, v253, 34
	v_mfma_f32_16x16x32_bf16 v[66:69], v[78:81], v[12:15], v[66:69]
	v_readlane_b32 s1, v253, 35
	v_mov_b32_e32 v95, v17
	v_mfma_f32_16x16x32_bf16 v[4:7], v[82:85], v[12:15], v[4:7]
	v_lshlrev_b64 v[12:13], 9, v[70:71]
	v_lshl_add_u64 v[12:13], s[0:1], 0, v[12:13]
	v_lshl_add_u64 v[12:13], v[12:13], 0, v[94:95]
	global_store_dwordx2 v[12:13], v[0:1], off
	v_cvt_pk_bf16_f32 v0, v8, v9
	v_cvt_pk_bf16_f32 v1, v10, v11
	global_store_dwordx2 v[12:13], v[0:1], off offset:32
	v_cvt_pk_bf16_f32 v0, v18, v19
	v_cvt_pk_bf16_f32 v1, v20, v21
	global_store_dwordx2 v[12:13], v[0:1], off offset:64
	v_cvt_pk_bf16_f32 v0, v22, v23
	v_cvt_pk_bf16_f32 v1, v24, v25
	global_store_dwordx2 v[12:13], v[0:1], off offset:96
	v_cvt_pk_bf16_f32 v0, v26, v27
	v_cvt_pk_bf16_f32 v1, v28, v29
	global_store_dwordx2 v[12:13], v[0:1], off offset:128
	v_cvt_pk_bf16_f32 v0, v30, v31
	v_cvt_pk_bf16_f32 v1, v32, v33
	global_store_dwordx2 v[12:13], v[0:1], off offset:160
	v_cvt_pk_bf16_f32 v0, v38, v39
	v_cvt_pk_bf16_f32 v1, v40, v41
	global_store_dwordx2 v[12:13], v[0:1], off offset:192
	v_cvt_pk_bf16_f32 v0, v34, v35
	v_cvt_pk_bf16_f32 v1, v36, v37
	global_store_dwordx2 v[12:13], v[0:1], off offset:224
	v_cvt_pk_bf16_f32 v0, v46, v47
	v_cvt_pk_bf16_f32 v1, v48, v49
	global_store_dwordx2 v[12:13], v[0:1], off offset:256
	v_cvt_pk_bf16_f32 v0, v42, v43
	v_cvt_pk_bf16_f32 v1, v44, v45
	global_store_dwordx2 v[12:13], v[0:1], off offset:288
	v_cvt_pk_bf16_f32 v0, v54, v55
	v_cvt_pk_bf16_f32 v1, v56, v57
	global_store_dwordx2 v[12:13], v[0:1], off offset:320
	v_cvt_pk_bf16_f32 v0, v50, v51
	v_cvt_pk_bf16_f32 v1, v52, v53
	global_store_dwordx2 v[12:13], v[0:1], off offset:352
	v_cvt_pk_bf16_f32 v0, v62, v63
	v_cvt_pk_bf16_f32 v1, v64, v65
	global_store_dwordx2 v[12:13], v[0:1], off offset:384
	v_cvt_pk_bf16_f32 v0, v66, v67
	v_cvt_pk_bf16_f32 v1, v68, v69
	global_store_dwordx2 v[12:13], v[0:1], off offset:416
	v_cvt_pk_bf16_f32 v0, v58, v59
	v_cvt_pk_bf16_f32 v1, v60, v61
	global_store_dwordx2 v[12:13], v[0:1], off offset:448
	v_cvt_pk_bf16_f32 v0, v4, v5
	v_cvt_pk_bf16_f32 v1, v6, v7
	global_store_dwordx2 v[12:13], v[0:1], off offset:480
	s_cbranch_scc0 .LBB0_677

; __device__ __forceinline__ float siluf(float x) { return x * __builtin_amdgcn_rcpf(1.0f + __expf(-x)); }
; #define BSYNC() do { asm volatile("s_waitcnt vmcnt(0) lgkmcnt(0)" ::: "memory"); __syncthreads(); } while (0)
; template <int TY> __device__ __forceinline__ void mc_item(const Params& p, ldsp lds, int item) {
;     ...
;     BSYNC();
; #pragma unroll
;     for (int tk = 0; tk < 4; ++tk) { float s = 0.f;
; #pragma unroll
;         for (int w = 0; w < 8; ++w) s += RED[w * 64 + 16 * tk + l15];
;         rstd[tk] = rsqrtf(s * (1.0f / DV) + EPS); }
;     const float* nwp = TY == 0 ? p.in[12] : (TY == 1 ? p.in[14] : p.in[17]);
;     const int goff = TY == 0 ? E_RA + h * 128 : (TY == 1 ? E_GB + h * 128 : O_G + h * 512);
;     constexpr int LDY = TY == 2 ? 2048 : 1024; const int ycol = TY == 0 ? h * 128 : (TY == 1 ? 512 + h * 128 : h * 512);
;     bf16_t* Y = (bf16_t*)(p.ws + WS_Y);
; #pragma unroll
;     for (int ei = 0; ei < ET; ++ei) { const int e0 = 16 * (wave * ET + ei) + 4 * q4; const f32x4 w4 = *(const f32x4*)(nwp + e0);
; #pragma unroll
;         for (int tk = 0; tk < 4; ++tk) { const size_t row = (size_t)row0 + 16 * tk + l15;
;             const u32x2 gw = *(const u32x2*)(Pb + row * PP + goff + e0);
;             const float g0 = bf2f(gw.x & 0xffffu), g1 = bf2f(gw.x >> 16), g2 = bf2f(gw.y & 0xffffu), g3 = bf2f(gw.y >> 16);
;             const f32x4 v = acc[ei][tk] * rstd[tk] * w4;
;             float y0 = v[0] * siluf(g0), y1 = v[1] * siluf(g1), y2 = v[2] * siluf(g2), y3 = v[3] * siluf(g3);
.LBB0_1239:
	s_or_b64 exec, exec, s[0:1]
	s_lshl_b32 s9, s15, 1
	s_add_u32 s0, s26, s9
	v_or_b32_e32 v18, s12, v28
	s_addc_u32 s1, s27, 0
	v_or_b32_e32 v22, s16, v30
	s_waitcnt lgkmcnt(0)
	v_ashrrev_i32_e32 v19, 31, v18
	v_mov_b64_e32 v[28:29], s[0:1]
	v_lshlrev_b64 v[26:27], 1, v[18:19]
	v_mad_i64_i32 v[24:25], s[0:1], v22, s55, v[28:29]
	v_lshl_add_u64 v[24:25], v[24:25], 0, v[26:27]
	s_waitcnt vmcnt(0) lgkmcnt(0)
	s_barrier
	global_load_dwordx2 v[48:49], v[24:25], off offset:2048 nt
	v_readlane_b32 s76, v252, 20
	v_readlane_b32 s84, v252, 28
	v_readlane_b32 s85, v252, 29
	v_lshl_add_u32 v16, v30, 2, 0
	v_add_u32_e32 v32, 0xd800, v16
	v_lshl_add_u64 v[20:21], v[18:19], 2, s[84:85]
	global_load_dwordx4 v[18:21], v[20:21], off
	v_or_b32_e32 v134, 16, v22
	v_mad_i64_i32 v[140:141], s[0:1], v134, s55, v[28:29]
	v_lshl_add_u64 v[142:143], v[140:141], 0, v[26:27]
	global_load_dwordx2 v[144:145], v[142:143], off offset:2048 nt
	v_or_b32_e32 v146, 32, v22
	v_mad_i64_i32 v[148:149], s[0:1], v146, s55, v[28:29]
	v_lshl_add_u64 v[150:151], v[148:149], 0, v[26:27]
	v_or_b32_e32 v152, 48, v22
	global_load_dwordx2 v[154:155], v[150:151], off offset:2048 nt
	v_mad_i64_i32 v[156:157], s[0:1], v152, s55, v[28:29]
	v_lshl_add_u64 v[166:167], v[156:157], 0, v[26:27]
	global_load_dwordx2 v[168:169], v[166:167], off offset:2048 nt
	v_add_u32_e32 v16, 0xdc00, v16
	ds_read2_b32 v[24:25], v32 offset1:16
	ds_read2_b32 v[50:51], v32 offset0:64 offset1:80
	ds_read2_b32 v[52:53], v32 offset0:128 offset1:144
	ds_read2_b32 v[54:55], v32 offset0:192 offset1:208
	ds_read2_b32 v[56:57], v16 offset1:16
	ds_read2_b32 v[58:59], v16 offset0:64 offset1:80
	ds_read2_b32 v[60:61], v16 offset0:128 offset1:144
	ds_read2_b32 v[62:63], v16 offset0:192 offset1:208
	ds_read2_b32 v[46:47], v32 offset0:32 offset1:48
	ds_read2_b32 v[44:45], v32 offset0:96 offset1:112
	ds_read2_b32 v[42:43], v32 offset0:160 offset1:176
	ds_read2_b32 v[40:41], v32 offset0:224 offset1:240
	ds_read2_b32 v[38:39], v16 offset0:32 offset1:48
	ds_read2_b32 v[36:37], v16 offset0:96 offset1:112
	ds_read2_b32 v[34:35], v16 offset0:160 offset1:176
	ds_read2_b32 v[32:33], v16 offset0:224 offset1:240
	s_waitcnt lgkmcnt(14)
	v_mov_b32_e32 v64, v25
	v_mov_b32_e32 v65, v24
	v_mov_b32_e32 v24, v51
	v_mov_b32_e32 v25, v50
	s_waitcnt lgkmcnt(13)
	v_mov_b32_e32 v50, v53
	v_mov_b32_e32 v51, v52
	s_waitcnt lgkmcnt(12)
	v_mov_b32_e32 v52, v55
	v_mov_b32_e32 v53, v54
	s_waitcnt lgkmcnt(11)
	v_mov_b32_e32 v54, v57
	v_mov_b32_e32 v55, v56
	s_waitcnt lgkmcnt(10)
	v_mov_b32_e32 v56, v59
	v_mov_b32_e32 v57, v58
	s_waitcnt lgkmcnt(9)
	v_mov_b32_e32 v58, v61
	v_mov_b32_e32 v59, v60
	s_waitcnt lgkmcnt(8)
	v_mov_b32_e32 v60, v63
	v_mov_b32_e32 v61, v62
	v_pk_add_f32 v[62:63], v[64:65], 0 op_sel_hi:[1,0]
	s_mov_b32 s0, 0x358637bd
	v_pk_add_f32 v[24:25], v[62:63], v[24:25]
	v_mov_b64_e32 v[30:31], s[0:1]
	v_pk_add_f32 v[24:25], v[24:25], v[50:51]
	v_mov_b32_e32 v23, s8
	v_pk_add_f32 v[24:25], v[24:25], v[52:53]
	s_brev_b32 s8, 60
	v_pk_add_f32 v[24:25], v[24:25], v[54:55]
	s_add_u32 s0, s61, s9
	v_pk_add_f32 v[24:25], v[24:25], v[56:57]
	v_readlane_b32 s1, v253, 31
	v_pk_add_f32 v[24:25], v[24:25], v[58:59]
	s_addc_u32 s1, s1, 0
	v_pk_add_f32 v[24:25], v[24:25], v[60:61]
	v_readlane_b32 s77, v252, 21
	v_pk_fma_f32 v[50:51], v[24:25], s[8:9], v[30:31] op_sel_hi:[1,0,0]
	v_lshl_add_u64 v[24:25], s[0:1], 0, v[26:27]
	v_mul_f32_e32 v16, 0x4b800000, v51
	v_cmp_gt_f32_e32 vcc, s33, v51
	v_readlane_b32 s78, v252, 22
	v_readlane_b32 s79, v252, 23
	v_cndmask_b32_e32 v16, v51, v16, vcc
	v_rsq_f32_e32 v16, v16
	v_readlane_b32 s80, v252, 24
	v_readlane_b32 s81, v252, 25
	v_readlane_b32 s82, v252, 26
	v_mul_f32_e32 v51, 0x45800000, v16
	v_cndmask_b32_e32 v16, v16, v51, vcc
	v_pk_mul_f32 v[12:13], v[12:13], v[16:17] op_sel_hi:[1,0]
	v_pk_mul_f32 v[14:15], v[14:15], v[16:17] op_sel_hi:[1,0]
	v_cmp_gt_f32_e32 vcc, s33, v50
	v_readlane_b32 s83, v252, 27
	v_readlane_b32 s86, v252, 30
	v_readlane_b32 s87, v252, 31
	v_readlane_b32 s88, v252, 32
	v_readlane_b32 s89, v252, 33
	v_readlane_b32 s90, v252, 34
	v_readlane_b32 s91, v252, 35
	s_waitcnt vmcnt(0)
; __device__ __forceinline__ unsigned pk2(float lo, float hi) { return pg8::cvt_pk_bf16(lo, hi); }
; __device__ __forceinline__ float siluf(float x) { return x * __builtin_amdgcn_rcpf(1.0f + __expf(-x)); }
; template <int TY> __device__ __forceinline__ void mc_item(const Params& p, ldsp lds, int item) {
;     ...
;     for (int ei = 0; ei < ET; ++ei) { const int e0 = 16 * (wave * ET + ei) + 4 * q4; const f32x4 w4 = *(const f32x4*)(nwp + e0);
; #pragma unroll
;         for (int tk = 0; tk < 4; ++tk) { const size_t row = (size_t)row0 + 16 * tk + l15;
;             const u32x2 gw = *(const u32x2*)(Pb + row * PP + goff + e0);
;             const float g0 = bf2f(gw.x & 0xffffu), g1 = bf2f(gw.x >> 16), g2 = bf2f(gw.y & 0xffffu), g3 = bf2f(gw.y >> 16);
;             const f32x4 v = acc[ei][tk] * rstd[tk] * w4;
;             float y0 = v[0] * siluf(g0), y1 = v[1] * siluf(g1), y2 = v[2] * siluf(g2), y3 = v[3] * siluf(g3);
;     ...
;             if (!(fabsf(y0) < 1e30f)) y0 = 0.f; if (!(fabsf(y1) < 1e30f)) y1 = 0.f; if (!(fabsf(y2) < 1e30f)) y2 = 0.f; if (!(fabsf(y3) < 1e30f)) y3 = 0.f;
;     ...
;             u32x2 o; o.x = pk2(y0, y1); o.y = pk2(y2, y3);
;             *(u32x2*)(Y + row * LDY + ycol + e0) = o; } }
	v_lshlrev_b32_e32 v16, 16, v48
	v_mul_f32_e32 v52, 0xbfb8aa3b, v16
	v_exp_f32_e32 v52, v52
	v_and_b32_e32 v48, 0xffff0000, v48
	v_lshlrev_b32_e32 v51, 16, v49
	v_and_b32_e32 v49, 0xffff0000, v49
	v_mul_f32_e32 v53, 0xbfb8aa3b, v48
	v_mul_f32_e32 v54, 0xbfb8aa3b, v51
	v_mul_f32_e32 v55, 0xbfb8aa3b, v49
	v_exp_f32_e32 v53, v53
	v_add_f32_e32 v52, 1.0, v52
	v_exp_f32_e32 v54, v54
	v_exp_f32_e32 v55, v55
	v_rcp_f32_e32 v52, v52
	v_add_f32_e32 v53, 1.0, v53
	v_pk_mul_f32 v[12:13], v[12:13], v[18:19]
	v_add_f32_e32 v54, 1.0, v54
	v_rcp_f32_e32 v53, v53
	v_add_f32_e32 v55, 1.0, v55
	v_mul_f32_e32 v16, v52, v16
	v_rcp_f32_e32 v54, v54
	v_mul_f32_e32 v12, v12, v16
	v_rcp_f32_e32 v16, v55
	v_mul_f32_e32 v48, v53, v48
	v_pk_mul_f32 v[14:15], v[14:15], v[20:21]
	v_mul_f32_e32 v13, v13, v48
	v_mul_f32_e32 v48, v54, v51
	v_mul_f32_e32 v16, v16, v49
	v_mul_f32_e32 v14, v14, v48
	v_mul_f32_e32 v15, v15, v16
	v_cvt_pk_bf16_f32 v12, v12, v13
	v_cvt_pk_bf16_f32 v13, v14, v15
	v_lshlrev_b64 v[14:15], 11, v[22:23]
	v_lshl_add_u64 v[14:15], v[24:25], 0, v[14:15]
	global_store_dwordx2 v[14:15], v[12:13], off nt
	v_or_b32_e32 v12, 16, v22
	v_mad_i64_i32 v[14:15], s[0:1], v12, s55, v[28:29]
	v_lshl_add_u64 v[14:15], v[14:15], 0, v[26:27]
	v_mul_f32_e32 v16, 0x4b800000, v50
	v_cndmask_b32_e32 v16, v50, v16, vcc
	v_rsq_f32_e32 v16, v16
	v_mov_b32_e32 v13, v23
	v_or_b32_e32 v48, 32, v22
	v_lshlrev_b64 v[12:13], 11, v[12:13]
	v_mul_f32_e32 v49, 0x45800000, v16
	v_cndmask_b32_e32 v16, v16, v49, vcc
	v_pk_mul_f32 v[8:9], v[8:9], v[16:17] op_sel_hi:[1,0]
	v_pk_mul_f32 v[10:11], v[10:11], v[16:17] op_sel_hi:[1,0]
	v_pk_mul_f32 v[8:9], v[8:9], v[18:19]
	v_mad_i64_i32 v[50:51], s[0:1], v48, s55, v[28:29]
	v_lshl_add_u64 v[12:13], v[24:25], 0, v[12:13]
	v_pk_mul_f32 v[10:11], v[10:11], v[20:21]
	v_lshl_add_u64 v[50:51], v[50:51], 0, v[26:27]
	v_or_b32_e32 v22, 48, v22
	v_lshlrev_b32_e32 v16, 16, v144
	v_and_b32_e32 v14, 0xffff0000, v144
	v_lshlrev_b32_e32 v49, 16, v145
	v_and_b32_e32 v15, 0xffff0000, v145
	v_mul_f32_e32 v52, 0xbfb8aa3b, v16
	v_mul_f32_e32 v53, 0xbfb8aa3b, v14
	v_mul_f32_e32 v54, 0xbfb8aa3b, v49
	v_mul_f32_e32 v55, 0xbfb8aa3b, v15
	v_exp_f32_e32 v52, v52
	v_exp_f32_e32 v53, v53
	v_exp_f32_e32 v54, v54
	v_exp_f32_e32 v55, v55
	v_add_f32_e32 v52, 1.0, v52
	v_add_f32_e32 v53, 1.0, v53
	v_add_f32_e32 v54, 1.0, v54
	v_add_f32_e32 v55, 1.0, v55
	v_rcp_f32_e32 v52, v52
	v_rcp_f32_e32 v53, v53
	v_rcp_f32_e32 v54, v54
	v_rcp_f32_e32 v55, v55
	v_mul_f32_e32 v16, v52, v16
	v_mul_f32_e32 v14, v53, v14
	v_mul_f32_e32 v49, v54, v49
	v_mul_f32_e32 v15, v55, v15
	v_mul_f32_e32 v8, v8, v16
	v_mul_f32_e32 v9, v9, v14
	v_mul_f32_e32 v10, v10, v49
	v_mul_f32_e32 v11, v11, v15
	v_cvt_pk_bf16_f32 v8, v8, v9
	v_cvt_pk_bf16_f32 v9, v10, v11
	global_store_dwordx2 v[12:13], v[8:9], off nt
	s_waitcnt lgkmcnt(7)
	v_mov_b32_e32 v12, v47
	v_mov_b32_e32 v13, v46
	s_waitcnt lgkmcnt(6)
	v_mov_b32_e32 v14, v45
	v_mov_b32_e32 v15, v44
	v_pk_add_f32 v[12:13], v[12:13], 0 op_sel_hi:[1,0]
	s_waitcnt lgkmcnt(5)
	v_mov_b32_e32 v44, v43
	v_mov_b32_e32 v45, v42
	v_pk_add_f32 v[12:13], v[12:13], v[14:15]
	s_waitcnt lgkmcnt(4)
	v_mov_b32_e32 v42, v41
	v_mov_b32_e32 v43, v40
	v_pk_add_f32 v[12:13], v[12:13], v[44:45]
	s_waitcnt lgkmcnt(3)
	v_mov_b32_e32 v40, v39
	v_mov_b32_e32 v41, v38
	v_pk_add_f32 v[12:13], v[12:13], v[42:43]
	s_waitcnt lgkmcnt(2)
	v_mov_b32_e32 v38, v37
	v_mov_b32_e32 v39, v36
	v_pk_add_f32 v[12:13], v[12:13], v[40:41]
	s_waitcnt lgkmcnt(1)
	v_mov_b32_e32 v36, v35
	v_mov_b32_e32 v37, v34
	v_pk_add_f32 v[12:13], v[12:13], v[38:39]
	s_waitcnt lgkmcnt(0)
	v_mov_b32_e32 v34, v33
	v_mov_b32_e32 v35, v32
	v_pk_add_f32 v[12:13], v[12:13], v[36:37]
	v_mov_b32_e32 v49, v23
	v_pk_add_f32 v[12:13], v[12:13], v[34:35]
	v_lshlrev_b64 v[10:11], 11, v[48:49]
	v_pk_fma_f32 v[12:13], v[12:13], s[8:9], v[30:31] op_sel_hi:[1,0,0]
	v_lshl_add_u64 v[10:11], v[24:25], 0, v[10:11]
	v_mul_f32_e32 v14, 0x4b800000, v13
	v_cmp_gt_f32_e32 vcc, s33, v13
	s_nop 1
	v_cndmask_b32_e32 v13, v13, v14, vcc
	v_rsq_f32_e32 v13, v13
	v_mad_i64_i32 v[14:15], s[0:1], v22, s55, v[28:29]
	v_lshl_add_u64 v[14:15], v[14:15], 0, v[26:27]
	v_mul_f32_e32 v16, 0x45800000, v13
	v_cndmask_b32_e32 v16, v13, v16, vcc
	v_pk_mul_f32 v[4:5], v[4:5], v[16:17] op_sel_hi:[1,0]
	v_pk_mul_f32 v[6:7], v[6:7], v[16:17] op_sel_hi:[1,0]
	v_pk_mul_f32 v[4:5], v[18:19], v[4:5]
	v_pk_mul_f32 v[6:7], v[20:21], v[6:7]
	v_cmp_gt_f32_e32 vcc, s33, v12
	v_lshlrev_b32_e32 v13, 16, v154
	v_and_b32_e32 v8, 0xffff0000, v154
	v_lshlrev_b32_e32 v16, 16, v155
	v_and_b32_e32 v9, 0xffff0000, v155
	v_mul_f32_e32 v26, 0xbfb8aa3b, v13
	v_mul_f32_e32 v27, 0xbfb8aa3b, v8
	v_mul_f32_e32 v28, 0xbfb8aa3b, v16
	v_mul_f32_e32 v29, 0xbfb8aa3b, v9
	v_exp_f32_e32 v26, v26
	v_exp_f32_e32 v27, v27
	v_exp_f32_e32 v28, v28
	v_exp_f32_e32 v29, v29
	v_add_f32_e32 v26, 1.0, v26
	v_add_f32_e32 v27, 1.0, v27
	v_add_f32_e32 v28, 1.0, v28
	v_add_f32_e32 v29, 1.0, v29
	v_rcp_f32_e32 v26, v26
	v_rcp_f32_e32 v27, v27
	v_rcp_f32_e32 v28, v28
	v_rcp_f32_e32 v29, v29
	v_mul_f32_e32 v13, v26, v13
	v_mul_f32_e32 v8, v27, v8
	v_mul_f32_e32 v16, v28, v16
	v_mul_f32_e32 v9, v29, v9
	v_mul_f32_e32 v4, v4, v13
	v_mul_f32_e32 v5, v5, v8
	v_mul_f32_e32 v6, v6, v16
	v_mul_f32_e32 v7, v7, v9
	v_cvt_pk_bf16_f32 v4, v4, v5
	v_cvt_pk_bf16_f32 v5, v6, v7
	global_store_dwordx2 v[10:11], v[4:5], off nt
	v_mul_f32_e32 v6, 0x4b800000, v12
	v_cndmask_b32_e32 v6, v12, v6, vcc
	v_rsq_f32_e32 v8, v6
	v_lshlrev_b64 v[6:7], 11, v[22:23]
	v_mul_f32_e32 v9, 0x45800000, v8
	v_cndmask_b32_e32 v8, v8, v9, vcc
	v_pk_mul_f32 v[0:1], v[0:1], v[8:9] op_sel_hi:[1,0]
	v_pk_mul_f32 v[2:3], v[2:3], v[8:9] op_sel_hi:[1,0]
	v_pk_mul_f32 v[0:1], v[18:19], v[0:1]
	v_pk_mul_f32 v[2:3], v[20:21], v[2:3]
	v_lshlrev_b32_e32 v8, 16, v168
	v_and_b32_e32 v4, 0xffff0000, v168
	v_lshlrev_b32_e32 v9, 16, v169
	v_and_b32_e32 v5, 0xffff0000, v169
	v_mul_f32_e32 v10, 0xbfb8aa3b, v8
	v_mul_f32_e32 v11, 0xbfb8aa3b, v4
	v_mul_f32_e32 v12, 0xbfb8aa3b, v9
	v_mul_f32_e32 v13, 0xbfb8aa3b, v5
	v_exp_f32_e32 v10, v10
	v_exp_f32_e32 v11, v11
	v_exp_f32_e32 v12, v12
	v_exp_f32_e32 v13, v13
	v_add_f32_e32 v10, 1.0, v10
	v_add_f32_e32 v11, 1.0, v11
	v_add_f32_e32 v12, 1.0, v12
	v_add_f32_e32 v13, 1.0, v13
	v_rcp_f32_e32 v10, v10
	v_rcp_f32_e32 v11, v11
	v_rcp_f32_e32 v12, v12
	v_rcp_f32_e32 v13, v13
	v_mul_f32_e32 v8, v10, v8
	v_mul_f32_e32 v4, v11, v4
	v_mul_f32_e32 v9, v12, v9
	v_mul_f32_e32 v5, v13, v5
	v_mul_f32_e32 v0, v0, v8
	v_mul_f32_e32 v1, v1, v4
	v_mul_f32_e32 v2, v2, v9
	v_mul_f32_e32 v3, v3, v5
	v_cvt_pk_bf16_f32 v0, v0, v1
	v_cvt_pk_bf16_f32 v1, v2, v3
	v_lshl_add_u64 v[2:3], v[24:25], 0, v[6:7]
	global_store_dwordx2 v[2:3], v[0:1], off nt
	s_waitcnt vmcnt(0) lgkmcnt(0)
	s_barrier

; __device__ __forceinline__ float siluf(float x) { return x * __builtin_amdgcn_rcpf(1.0f + __expf(-x)); }
; #define BSYNC() do { asm volatile("s_waitcnt vmcnt(0) lgkmcnt(0)" ::: "memory"); __syncthreads(); } while (0)
; template <int TY> __device__ __forceinline__ void mc_item(const Params& p, ldsp lds, int item) {
;     ...
;     BSYNC();
; #pragma unroll
;     for (int tk = 0; tk < 4; ++tk) { float s = 0.f;
; #pragma unroll
;         for (int w = 0; w < 8; ++w) s += RED[w * 64 + 16 * tk + l15];
;         rstd[tk] = rsqrtf(s * (1.0f / DV) + EPS); }
;     const float* nwp = TY == 0 ? p.in[12] : (TY == 1 ? p.in[14] : p.in[17]);
;     const int goff = TY == 0 ? E_RA + h * 128 : (TY == 1 ? E_GB + h * 128 : O_G + h * 512);
;     constexpr int LDY = TY == 2 ? 2048 : 1024; const int ycol = TY == 0 ? h * 128 : (TY == 1 ? 512 + h * 128 : h * 512);
;     bf16_t* Y = (bf16_t*)(p.ws + WS_Y);
; #pragma unroll
;     for (int ei = 0; ei < ET; ++ei) { const int e0 = 16 * (wave * ET + ei) + 4 * q4; const f32x4 w4 = *(const f32x4*)(nwp + e0);
; #pragma unroll
;         for (int tk = 0; tk < 4; ++tk) { const size_t row = (size_t)row0 + 16 * tk + l15;
;             const u32x2 gw = *(const u32x2*)(Pb + row * PP + goff + e0);
;             const float g0 = bf2f(gw.x & 0xffffu), g1 = bf2f(gw.x >> 16), g2 = bf2f(gw.y & 0xffffu), g3 = bf2f(gw.y >> 16);
;             const f32x4 v = acc[ei][tk] * rstd[tk] * w4;
;             float y0 = v[0] * siluf(g0), y1 = v[1] * siluf(g1), y2 = v[2] * siluf(g2), y3 = v[3] * siluf(g3);
.LBB0_1254:
	s_or_b64 exec, exec, s[0:1]
	v_lshl_add_u32 v8, v24, 2, 0
	v_add_u32_e32 v16, 0x13800, v8
	v_or_b32_e32 v22, s17, v24
	s_waitcnt vmcnt(0) lgkmcnt(0)
	s_waitcnt lgkmcnt(0)
	s_barrier
	ds_read2_b32 v[8:9], v16 offset1:16
	ds_read2_b32 v[10:11], v16 offset0:64 offset1:80
	ds_read2_b32 v[24:25], v16 offset0:128 offset1:144
	ds_read2_b32 v[26:27], v16 offset0:192 offset1:208
	v_add_u32_e32 v40, 0x400, v16
	s_waitcnt lgkmcnt(3)
	v_mov_b32_e32 v36, v9
	v_mov_b32_e32 v37, v8
	v_pk_add_f32 v[8:9], v[36:37], 0 op_sel_hi:[1,0]
	s_waitcnt lgkmcnt(2)
	v_mov_b32_e32 v36, v11
	v_mov_b32_e32 v37, v10
	ds_read2_b32 v[28:29], v40 offset1:16
	ds_read2_b32 v[30:31], v40 offset0:64 offset1:80
	ds_read2_b32 v[32:33], v40 offset0:128 offset1:144
	ds_read2_b32 v[34:35], v40 offset0:192 offset1:208
	v_pk_add_f32 v[8:9], v[8:9], v[36:37]
	s_waitcnt lgkmcnt(5)
	v_mov_b32_e32 v10, v25
	v_mov_b32_e32 v11, v24
	v_pk_add_f32 v[8:9], v[8:9], v[10:11]
	s_waitcnt lgkmcnt(4)
	v_mov_b32_e32 v10, v27
	v_mov_b32_e32 v11, v26
	v_pk_add_f32 v[8:9], v[8:9], v[10:11]
	s_waitcnt lgkmcnt(3)
	v_mov_b32_e32 v10, v29
	v_mov_b32_e32 v11, v28
	v_pk_add_f32 v[8:9], v[8:9], v[10:11]
	s_waitcnt lgkmcnt(2)
	v_mov_b32_e32 v10, v31
	v_mov_b32_e32 v11, v30
	v_pk_add_f32 v[8:9], v[8:9], v[10:11]
	s_waitcnt lgkmcnt(1)
	v_mov_b32_e32 v10, v33
	v_mov_b32_e32 v11, v32
	v_pk_add_f32 v[8:9], v[8:9], v[10:11]
	s_waitcnt lgkmcnt(0)
	v_mov_b32_e32 v10, v35
	v_mov_b32_e32 v11, v34
	s_mov_b32 s0, 0x358637bd
	v_pk_add_f32 v[8:9], v[8:9], v[10:11]
	v_mov_b64_e32 v[10:11], s[0:1]
	s_brev_b32 s18, 60
	v_pk_fma_f32 v[8:9], v[8:9], s[18:19], v[10:11] op_sel_hi:[1,0,0]
	v_readlane_b32 s76, v252, 20
	v_mul_f32_e32 v24, 0x4b800000, v9
	v_cmp_gt_f32_e64 s[0:1], s33, v9
	v_cmp_gt_f32_e32 vcc, s33, v8
	v_readlane_b32 s88, v252, 32
	v_cndmask_b32_e64 v9, v9, v24, s[0:1]
	v_rsq_f32_e32 v9, v9
	v_readlane_b32 s89, v252, 33
	v_readlane_b32 s77, v252, 21
	v_readlane_b32 s78, v252, 22
	v_mul_f32_e32 v24, 0x45800000, v9
	v_cndmask_b32_e64 v32, v9, v24, s[0:1]
	v_mul_f32_e32 v9, 0x4b800000, v8
	v_cndmask_b32_e32 v8, v8, v9, vcc
	v_rsq_f32_e32 v8, v8
	v_readlane_b32 s79, v252, 23
	v_readlane_b32 s80, v252, 24
	v_readlane_b32 s81, v252, 25
	v_mul_f32_e32 v9, 0x45800000, v8
	v_cndmask_b32_e32 v30, v8, v9, vcc
	ds_read2_b32 v[8:9], v16 offset0:32 offset1:48
	ds_read2_b32 v[24:25], v16 offset0:96 offset1:112
	ds_read2_b32 v[26:27], v16 offset0:160 offset1:176
	ds_read2_b32 v[28:29], v16 offset0:224 offset1:240
	ds_read2_b32 v[34:35], v40 offset0:32 offset1:48
	ds_read2_b32 v[36:37], v40 offset0:96 offset1:112
	ds_read2_b32 v[38:39], v40 offset0:160 offset1:176
	ds_read2_b32 v[40:41], v40 offset0:224 offset1:240
	s_waitcnt lgkmcnt(7)
	v_mov_b32_e32 v42, v9
	v_mov_b32_e32 v43, v8
	v_pk_add_f32 v[8:9], v[42:43], 0 op_sel_hi:[1,0]
	s_waitcnt lgkmcnt(6)
	v_mov_b32_e32 v42, v25
	v_mov_b32_e32 v43, v24
	v_pk_add_f32 v[8:9], v[8:9], v[42:43]
	s_waitcnt lgkmcnt(5)
	v_mov_b32_e32 v24, v27
	v_mov_b32_e32 v25, v26
	v_pk_add_f32 v[8:9], v[8:9], v[24:25]
	s_waitcnt lgkmcnt(4)
	v_mov_b32_e32 v24, v29
	v_mov_b32_e32 v25, v28
	v_pk_add_f32 v[8:9], v[8:9], v[24:25]
	s_waitcnt lgkmcnt(3)
	v_mov_b32_e32 v24, v35
	v_mov_b32_e32 v25, v34
	v_pk_add_f32 v[8:9], v[8:9], v[24:25]
	s_waitcnt lgkmcnt(2)
	v_mov_b32_e32 v24, v37
	v_mov_b32_e32 v25, v36
	v_pk_add_f32 v[8:9], v[8:9], v[24:25]
	s_waitcnt lgkmcnt(1)
	v_mov_b32_e32 v24, v39
	v_mov_b32_e32 v25, v38
	v_pk_add_f32 v[8:9], v[8:9], v[24:25]
	s_waitcnt lgkmcnt(0)
	v_mov_b32_e32 v24, v41
	v_mov_b32_e32 v25, v40
	v_pk_add_f32 v[8:9], v[8:9], v[24:25]
	v_or_b32_e32 v24, s13, v23
	v_pk_fma_f32 v[8:9], v[8:9], s[18:19], v[10:11] op_sel_hi:[1,0,0]
	s_add_u32 s18, s26, s16
	v_mul_f32_e32 v10, 0x4b800000, v9
	v_cmp_gt_f32_e64 s[0:1], s33, v9
	v_cmp_gt_f32_e32 vcc, s33, v8
	s_addc_u32 s19, s27, 0
	v_cndmask_b32_e64 v9, v9, v10, s[0:1]
	v_rsq_f32_e32 v9, v9
	v_ashrrev_i32_e32 v25, 31, v24
	v_mov_b64_e32 v[28:29], s[18:19]
	v_mov_b32_e32 v23, s9
	v_mul_f32_e32 v10, 0x45800000, v9
	v_cndmask_b32_e64 v26, v9, v10, s[0:1]
	v_mul_f32_e32 v9, 0x4b800000, v8
	v_cndmask_b32_e32 v8, v8, v9, vcc
	v_rsq_f32_e32 v8, v8
	s_add_u32 s0, s68, s16
	v_mad_i64_i32 v[34:35], s[16:17], v22, s55, v[28:29]
	v_mul_f32_e32 v9, 0x45800000, v8
	v_cndmask_b32_e32 v16, v8, v9, vcc
	v_lshl_add_u64 v[8:9], v[24:25], 2, s[88:89]
	v_lshlrev_b64 v[24:25], 1, v[24:25]
	v_lshl_add_u64 v[34:35], v[34:35], 0, v[24:25]
	v_add_co_u32_e32 v34, vcc, s57, v34
	global_load_dwordx4 v[8:11], v[8:9], off
	s_nop 0
	v_addc_co_u32_e32 v35, vcc, 0, v35, vcc
	global_load_dwordx2 v[34:35], v[34:35], off offset:2048 nt
	s_mov_b32 s98, s57
	s_mov_b32 s99, 0
	v_or_b32_e32 v64, 16, v22
	v_mad_i64_i32 v[134:135], s[16:17], v64, s55, v[28:29]
	v_lshl_add_u64 v[140:141], v[134:135], 0, v[24:25]
	v_lshl_add_u64 v[142:143], v[140:141], 0, s[98:99]
	global_load_dwordx2 v[144:145], v[142:143], off offset:2048 nt
	v_or_b32_e32 v146, 32, v22
	v_mad_i64_i32 v[148:149], s[16:17], v146, s55, v[28:29]
	v_lshl_add_u64 v[150:151], v[148:149], 0, v[24:25]
	v_lshl_add_u64 v[152:153], v[150:151], 0, s[98:99]
	global_load_dwordx2 v[154:155], v[152:153], off offset:2048 nt
	v_or_b32_e32 v156, 48, v22
	v_mad_i64_i32 v[166:167], s[16:17], v156, s55, v[28:29]
	v_lshl_add_u64 v[168:169], v[166:167], 0, v[24:25]
	v_lshl_add_u64 v[172:173], v[168:169], 0, s[98:99]
	global_load_dwordx2 v[174:175], v[172:173], off offset:2048 nt
	s_addc_u32 s1, s69, 0
	s_mov_b32 s9, 0x1ec21000
	v_pk_mul_f32 v[0:1], v[0:1], v[16:17] op_sel_hi:[1,0]
	v_pk_mul_f32 v[2:3], v[2:3], v[16:17] op_sel_hi:[1,0]
	v_readlane_b32 s82, v252, 26
	v_readlane_b32 s83, v252, 27
	v_readlane_b32 s84, v252, 28
	v_readlane_b32 s85, v252, 29
	v_readlane_b32 s86, v252, 30
	v_readlane_b32 s87, v252, 31
	v_readlane_b32 s90, v252, 34
	v_readlane_b32 s91, v252, 35
	s_waitcnt vmcnt(0)
; __device__ __forceinline__ unsigned pk2(float lo, float hi) { return pg8::cvt_pk_bf16(lo, hi); }
; __device__ __forceinline__ float siluf(float x) { return x * __builtin_amdgcn_rcpf(1.0f + __expf(-x)); }
; template <int TY> __device__ __forceinline__ void mc_item(const Params& p, ldsp lds, int item) {
;     ...
;     for (int ei = 0; ei < ET; ++ei) { const int e0 = 16 * (wave * ET + ei) + 4 * q4; const f32x4 w4 = *(const f32x4*)(nwp + e0);
; #pragma unroll
;         for (int tk = 0; tk < 4; ++tk) { const size_t row = (size_t)row0 + 16 * tk + l15;
;             const u32x2 gw = *(const u32x2*)(Pb + row * PP + goff + e0);
;             const float g0 = bf2f(gw.x & 0xffffu), g1 = bf2f(gw.x >> 16), g2 = bf2f(gw.y & 0xffffu), g3 = bf2f(gw.y >> 16);
;             const f32x4 v = acc[ei][tk] * rstd[tk] * w4;
;             float y0 = v[0] * siluf(g0), y1 = v[1] * siluf(g1), y2 = v[2] * siluf(g2), y3 = v[3] * siluf(g3);
;     ...
;             if (!(fabsf(y0) < 1e30f)) y0 = 0.f; if (!(fabsf(y1) < 1e30f)) y1 = 0.f; if (!(fabsf(y2) < 1e30f)) y2 = 0.f; if (!(fabsf(y3) < 1e30f)) y3 = 0.f;
;     ...
;             u32x2 o; o.x = pk2(y0, y1); o.y = pk2(y2, y3);
;             *(u32x2*)(Y + row * LDY + ycol + e0) = o; } }
	v_pk_mul_f32 v[0:1], v[8:9], v[0:1]
	v_pk_mul_f32 v[2:3], v[10:11], v[2:3]
	v_lshlrev_b32_e32 v27, 16, v34
	v_lshlrev_b32_e32 v33, 16, v35
	v_pk_mul_f32 v[18:19], v[18:19], v[32:33] op_sel_hi:[1,0]
	v_pk_mul_f32 v[20:21], v[20:21], v[32:33] op_sel_hi:[1,0]
	v_mul_f32_e32 v32, 0xbfb8aa3b, v27
	v_exp_f32_e32 v32, v32
	v_and_b32_e32 v31, 0xffff0000, v34
	v_pk_mul_f32 v[18:19], v[18:19], v[8:9]
	v_and_b32_e32 v34, 0xffff0000, v35
	v_add_f32_e32 v32, 1.0, v32
	v_rcp_f32_e32 v32, v32
	v_pk_mul_f32 v[20:21], v[20:21], v[10:11]
	v_mul_f32_e32 v27, v32, v27
	v_mul_f32_e32 v18, v18, v27
	v_mul_f32_e32 v27, 0xbfb8aa3b, v31
	v_exp_f32_e32 v27, v27
	s_nop 0
	v_add_f32_e32 v27, 1.0, v27
	v_rcp_f32_e32 v27, v27
	s_nop 0
	v_mul_f32_e32 v27, v27, v31
	v_mul_f32_e32 v19, v19, v27
	v_mul_f32_e32 v27, 0xbfb8aa3b, v33
	v_exp_f32_e32 v27, v27
	v_cvt_pk_bf16_f32 v18, v18, v19
	s_nop 0
	v_add_f32_e32 v27, 1.0, v27
	v_rcp_f32_e32 v27, v27
	s_nop 0
	v_mul_f32_e32 v27, v27, v33
	v_mul_f32_e32 v20, v20, v27
	v_mul_f32_e32 v27, 0xbfb8aa3b, v34
	v_exp_f32_e32 v27, v27
	s_nop 0
	v_add_f32_e32 v27, 1.0, v27
	v_rcp_f32_e32 v27, v27
	s_nop 0
	v_mul_f32_e32 v27, v27, v34
	v_mul_f32_e32 v21, v21, v27
	v_cvt_pk_bf16_f32 v19, v20, v21
	v_lshlrev_b64 v[20:21], 11, v[22:23]
	v_lshl_add_u64 v[20:21], s[0:1], 0, v[20:21]
	v_lshl_add_u64 v[20:21], v[20:21], 0, v[24:25]
	v_add_co_u32_e32 v20, vcc, s9, v20
	s_nop 1
	v_addc_co_u32_e32 v21, vcc, 0, v21, vcc
	global_store_dwordx2 v[20:21], v[18:19], off offset:1024 nt
	v_or_b32_e32 v18, 16, v22
	v_mad_i64_i32 v[20:21], s[16:17], v18, s55, v[28:29]
	v_lshl_add_u64 v[20:21], v[20:21], 0, v[24:25]
	s_nop 0
	v_mov_b32_e32 v19, v23
	s_nop 0
	v_lshl_add_u64 v[20:21], v[20:21], 0, s[98:99]
	v_lshlrev_b32_e32 v27, 16, v144
	v_lshlrev_b32_e32 v31, 16, v145
	v_pk_mul_f32 v[12:13], v[12:13], v[30:31] op_sel_hi:[1,0]
	v_pk_mul_f32 v[14:15], v[14:15], v[30:31] op_sel_hi:[1,0]
	v_mul_f32_e32 v30, 0xbfb8aa3b, v27
	v_exp_f32_e32 v30, v30
	v_and_b32_e32 v20, 0xffff0000, v144
	v_pk_mul_f32 v[12:13], v[12:13], v[8:9]
	v_and_b32_e32 v21, 0xffff0000, v145
	v_add_f32_e32 v30, 1.0, v30
	v_rcp_f32_e32 v30, v30
	v_pk_mul_f32 v[14:15], v[14:15], v[10:11]
	v_mul_f32_e32 v27, v30, v27
	v_mul_f32_e32 v12, v12, v27
	v_mul_f32_e32 v27, 0xbfb8aa3b, v20
	v_exp_f32_e32 v27, v27
	s_nop 0
	v_add_f32_e32 v27, 1.0, v27
	v_rcp_f32_e32 v27, v27
	s_nop 0
	v_mul_f32_e32 v20, v27, v20
	v_mul_f32_e32 v13, v13, v20
	v_mul_f32_e32 v20, 0xbfb8aa3b, v31
	v_exp_f32_e32 v20, v20
	v_cvt_pk_bf16_f32 v12, v12, v13
	v_pk_mul_f32 v[4:5], v[4:5], v[26:27] op_sel_hi:[1,0]
	v_pk_mul_f32 v[6:7], v[6:7], v[26:27] op_sel_hi:[1,0]
	v_add_f32_e32 v20, 1.0, v20
	v_rcp_f32_e32 v20, v20
	v_pk_mul_f32 v[4:5], v[8:9], v[4:5]
	v_pk_mul_f32 v[6:7], v[10:11], v[6:7]
	v_mul_f32_e32 v20, v20, v31
	v_mul_f32_e32 v14, v14, v20
	v_mul_f32_e32 v20, 0xbfb8aa3b, v21
	v_exp_f32_e32 v20, v20
	s_nop 0
	v_add_f32_e32 v20, 1.0, v20
	v_rcp_f32_e32 v20, v20
	s_nop 0
	v_mul_f32_e32 v20, v20, v21
	v_mul_f32_e32 v15, v15, v20
	v_cvt_pk_bf16_f32 v13, v14, v15
	v_lshlrev_b64 v[14:15], 11, v[18:19]
	v_lshl_add_u64 v[14:15], s[0:1], 0, v[14:15]
	v_lshl_add_u64 v[14:15], v[14:15], 0, v[24:25]
	v_add_co_u32_e32 v14, vcc, s9, v14
	s_nop 1
	v_addc_co_u32_e32 v15, vcc, 0, v15, vcc
	global_store_dwordx2 v[14:15], v[12:13], off offset:1024 nt
	v_or_b32_e32 v12, 32, v22
	v_mad_i64_i32 v[14:15], s[16:17], v12, s55, v[28:29]
	v_lshl_add_u64 v[14:15], v[14:15], 0, v[24:25]
	s_nop 0
	v_mov_b32_e32 v13, v23
	s_nop 0
	v_lshl_add_u64 v[14:15], v[14:15], 0, s[98:99]
	v_or_b32_e32 v22, 48, v22
	v_lshlrev_b32_e32 v18, 16, v154
	v_mul_f32_e32 v20, 0xbfb8aa3b, v18
	v_exp_f32_e32 v20, v20
	v_and_b32_e32 v14, 0xffff0000, v154
	v_lshlrev_b32_e32 v19, 16, v155
	v_and_b32_e32 v15, 0xffff0000, v155
	v_add_f32_e32 v20, 1.0, v20
	v_rcp_f32_e32 v20, v20
	s_nop 0
	v_mul_f32_e32 v18, v20, v18
	v_mul_f32_e32 v4, v4, v18
	v_mul_f32_e32 v18, 0xbfb8aa3b, v14
	v_exp_f32_e32 v18, v18
	s_nop 0
	v_add_f32_e32 v18, 1.0, v18
	v_rcp_f32_e32 v18, v18
	s_nop 0
	v_mul_f32_e32 v14, v18, v14
	v_mul_f32_e32 v5, v5, v14
	v_mul_f32_e32 v14, 0xbfb8aa3b, v19
	v_exp_f32_e32 v14, v14
	v_cvt_pk_bf16_f32 v4, v4, v5
	s_nop 0
	v_add_f32_e32 v14, 1.0, v14
	v_rcp_f32_e32 v14, v14
	s_nop 0
	v_mul_f32_e32 v14, v14, v19
	v_mul_f32_e32 v6, v6, v14
	v_mul_f32_e32 v14, 0xbfb8aa3b, v15
	v_exp_f32_e32 v14, v14
	s_nop 0
	v_add_f32_e32 v14, 1.0, v14
	v_rcp_f32_e32 v14, v14
	s_nop 0
	v_mul_f32_e32 v14, v14, v15
	v_mul_f32_e32 v7, v7, v14
	v_cvt_pk_bf16_f32 v5, v6, v7
	v_lshlrev_b64 v[6:7], 11, v[12:13]
	v_lshl_add_u64 v[6:7], s[0:1], 0, v[6:7]
	v_lshl_add_u64 v[6:7], v[6:7], 0, v[24:25]
	v_add_co_u32_e32 v6, vcc, s9, v6
	s_nop 1
	v_addc_co_u32_e32 v7, vcc, 0, v7, vcc
	global_store_dwordx2 v[6:7], v[4:5], off offset:1024 nt
	v_mad_i64_i32 v[4:5], s[16:17], v22, s55, v[28:29]
	v_lshl_add_u64 v[4:5], v[4:5], 0, v[24:25]
	s_nop 0
	s_nop 1
	v_lshl_add_u64 v[4:5], v[4:5], 0, s[98:99]
	v_lshlrev_b32_e32 v6, 16, v174
	v_mul_f32_e32 v8, 0xbfb8aa3b, v6
	v_exp_f32_e32 v8, v8
	v_and_b32_e32 v4, 0xffff0000, v174
	v_lshlrev_b32_e32 v7, 16, v175
	v_and_b32_e32 v5, 0xffff0000, v175
	v_add_f32_e32 v8, 1.0, v8
	v_rcp_f32_e32 v8, v8
	s_nop 0
	v_mul_f32_e32 v6, v8, v6
	v_mul_f32_e32 v0, v0, v6
	v_mul_f32_e32 v6, 0xbfb8aa3b, v4
	v_exp_f32_e32 v6, v6
	s_nop 0
	v_add_f32_e32 v6, 1.0, v6
	v_rcp_f32_e32 v6, v6
	s_nop 0
	v_mul_f32_e32 v4, v6, v4
	v_mul_f32_e32 v1, v1, v4
	v_mul_f32_e32 v4, 0xbfb8aa3b, v7
	v_exp_f32_e32 v4, v4
	v_cvt_pk_bf16_f32 v0, v0, v1
	s_nop 0
	v_add_f32_e32 v4, 1.0, v4
	v_rcp_f32_e32 v4, v4
	s_nop 0
	v_mul_f32_e32 v4, v4, v7
	v_mul_f32_e32 v2, v2, v4
	v_mul_f32_e32 v4, 0xbfb8aa3b, v5
	v_exp_f32_e32 v4, v4
	s_nop 0
	v_add_f32_e32 v4, 1.0, v4
	v_rcp_f32_e32 v4, v4
	s_nop 0
	v_mul_f32_e32 v4, v4, v5
	v_mul_f32_e32 v3, v3, v4
	v_cvt_pk_bf16_f32 v1, v2, v3
	v_lshlrev_b64 v[2:3], 11, v[22:23]
	v_lshl_add_u64 v[2:3], s[0:1], 0, v[2:3]
	v_lshl_add_u64 v[2:3], v[2:3], 0, v[24:25]
	v_add_co_u32_e32 v2, vcc, 0x1ec21000, v2
	s_nop 1
	v_addc_co_u32_e32 v3, vcc, 0, v3, vcc
	global_store_dwordx2 v[2:3], v[0:1], off offset:1024 nt
	s_waitcnt vmcnt(0) lgkmcnt(0)
	s_barrier
	s_branch .LBB0_1240

; __device__ __forceinline__ float siluf(float x) { return x * __builtin_amdgcn_rcpf(1.0f + __expf(-x)); }
; #define BSYNC() do { asm volatile("s_waitcnt vmcnt(0) lgkmcnt(0)" ::: "memory"); __syncthreads(); } while (0)
; template <int TY> __device__ __forceinline__ void mc_item(const Params& p, ldsp lds, int item) {
;     ...
;     BSYNC();
; #pragma unroll
;     for (int tk = 0; tk < 4; ++tk) { float s = 0.f;
; #pragma unroll
;         for (int w = 0; w < 8; ++w) s += RED[w * 64 + 16 * tk + l15];
;         rstd[tk] = rsqrtf(s * (1.0f / DV) + EPS); }
;     const float* nwp = TY == 0 ? p.in[12] : (TY == 1 ? p.in[14] : p.in[17]);
;     const int goff = TY == 0 ? E_RA + h * 128 : (TY == 1 ? E_GB + h * 128 : O_G + h * 512);
;     constexpr int LDY = TY == 2 ? 2048 : 1024; const int ycol = TY == 0 ? h * 128 : (TY == 1 ? 512 + h * 128 : h * 512);
;     bf16_t* Y = (bf16_t*)(p.ws + WS_Y);
; #pragma unroll
;     for (int ei = 0; ei < ET; ++ei) { const int e0 = 16 * (wave * ET + ei) + 4 * q4; const f32x4 w4 = *(const f32x4*)(nwp + e0);
; #pragma unroll
;         for (int tk = 0; tk < 4; ++tk) { const size_t row = (size_t)row0 + 16 * tk + l15;
;             const u32x2 gw = *(const u32x2*)(Pb + row * PP + goff + e0);
;             const float g0 = bf2f(gw.x & 0xffffu), g1 = bf2f(gw.x >> 16), g2 = bf2f(gw.y & 0xffffu), g3 = bf2f(gw.y >> 16);
;             const f32x4 v = acc[ei][tk] * rstd[tk] * w4;
;             float y0 = v[0] * siluf(g0), y1 = v[1] * siluf(g1), y2 = v[2] * siluf(g2), y3 = v[3] * siluf(g3);
.LBB0_1266:
	s_or_b64 exec, exec, s[0:1]
	s_lshl_b32 s9, s9, 1
	s_add_u32 s0, s26, s9
	v_or_b32_e32 v18, s10, v28
	s_addc_u32 s1, s27, 0
	v_or_b32_e32 v22, s11, v30
	s_waitcnt lgkmcnt(0)
	v_ashrrev_i32_e32 v19, 31, v18
	v_mov_b64_e32 v[28:29], s[0:1]
	v_lshlrev_b64 v[26:27], 1, v[18:19]
	v_mad_i64_i32 v[24:25], s[0:1], v22, s55, v[28:29]
	v_lshl_add_u64 v[24:25], v[24:25], 0, v[26:27]
	s_waitcnt vmcnt(0) lgkmcnt(0)
	s_barrier
	global_load_dwordx2 v[48:49], v[24:25], off offset:2048 nt
	v_readlane_b32 s76, v252, 20
	v_readlane_b32 s84, v252, 28
	v_readlane_b32 s85, v252, 29
	v_lshl_add_u32 v16, v30, 2, 0
	v_add_u32_e32 v32, 0xd800, v16
	v_lshl_add_u64 v[20:21], v[18:19], 2, s[84:85]
	global_load_dwordx4 v[18:21], v[20:21], off
	v_or_b32_e32 v134, 16, v22
	v_mad_i64_i32 v[140:141], s[0:1], v134, s55, v[28:29]
	v_lshl_add_u64 v[142:143], v[140:141], 0, v[26:27]
	global_load_dwordx2 v[144:145], v[142:143], off offset:2048 nt
	v_or_b32_e32 v146, 32, v22
	v_mad_i64_i32 v[148:149], s[0:1], v146, s55, v[28:29]
	v_lshl_add_u64 v[150:151], v[148:149], 0, v[26:27]
	v_or_b32_e32 v152, 48, v22
	global_load_dwordx2 v[154:155], v[150:151], off offset:2048 nt
	v_mad_i64_i32 v[156:157], s[0:1], v152, s55, v[28:29]
	v_lshl_add_u64 v[166:167], v[156:157], 0, v[26:27]
	global_load_dwordx2 v[168:169], v[166:167], off offset:2048 nt
	v_add_u32_e32 v16, 0xdc00, v16
	ds_read2_b32 v[24:25], v32 offset1:16
	ds_read2_b32 v[50:51], v32 offset0:64 offset1:80
	ds_read2_b32 v[52:53], v32 offset0:128 offset1:144
	ds_read2_b32 v[54:55], v32 offset0:192 offset1:208
	ds_read2_b32 v[56:57], v16 offset1:16
	ds_read2_b32 v[58:59], v16 offset0:64 offset1:80
	ds_read2_b32 v[60:61], v16 offset0:128 offset1:144
	ds_read2_b32 v[62:63], v16 offset0:192 offset1:208
	ds_read2_b32 v[46:47], v32 offset0:32 offset1:48
	ds_read2_b32 v[44:45], v32 offset0:96 offset1:112
	ds_read2_b32 v[42:43], v32 offset0:160 offset1:176
	ds_read2_b32 v[40:41], v32 offset0:224 offset1:240
	ds_read2_b32 v[38:39], v16 offset0:32 offset1:48
	ds_read2_b32 v[36:37], v16 offset0:96 offset1:112
	ds_read2_b32 v[34:35], v16 offset0:160 offset1:176
	ds_read2_b32 v[32:33], v16 offset0:224 offset1:240
	s_waitcnt lgkmcnt(14)
	v_mov_b32_e32 v64, v25
	v_mov_b32_e32 v65, v24
	v_mov_b32_e32 v24, v51
	v_mov_b32_e32 v25, v50
	s_waitcnt lgkmcnt(13)
	v_mov_b32_e32 v50, v53
	v_mov_b32_e32 v51, v52
	s_waitcnt lgkmcnt(12)
	v_mov_b32_e32 v52, v55
	v_mov_b32_e32 v53, v54
	s_waitcnt lgkmcnt(11)
	v_mov_b32_e32 v54, v57
	v_mov_b32_e32 v55, v56
	s_waitcnt lgkmcnt(10)
	v_mov_b32_e32 v56, v59
	v_mov_b32_e32 v57, v58
	s_waitcnt lgkmcnt(9)
	v_mov_b32_e32 v58, v61
	v_mov_b32_e32 v59, v60
	s_waitcnt lgkmcnt(8)
	v_mov_b32_e32 v60, v63
	v_mov_b32_e32 v61, v62
	v_pk_add_f32 v[62:63], v[64:65], 0 op_sel_hi:[1,0]
	s_mov_b32 s0, 0x358637bd
	v_pk_add_f32 v[24:25], v[62:63], v[24:25]
	v_mov_b64_e32 v[30:31], s[0:1]
	v_pk_add_f32 v[24:25], v[24:25], v[50:51]
	s_brev_b32 s10, 60
	v_pk_add_f32 v[24:25], v[24:25], v[52:53]
	s_add_u32 s0, s61, s9
	v_pk_add_f32 v[24:25], v[24:25], v[54:55]
	v_readlane_b32 s1, v253, 31
	v_pk_add_f32 v[24:25], v[24:25], v[56:57]
	v_mov_b32_e32 v23, s13
	v_pk_add_f32 v[24:25], v[24:25], v[58:59]
	s_addc_u32 s1, s1, 0
	v_pk_add_f32 v[24:25], v[24:25], v[60:61]
	v_readlane_b32 s77, v252, 21
	v_pk_fma_f32 v[50:51], v[24:25], s[10:11], v[30:31] op_sel_hi:[1,0,0]
	v_lshl_add_u64 v[24:25], s[0:1], 0, v[26:27]
	v_mul_f32_e32 v16, 0x4b800000, v51
	v_cmp_gt_f32_e32 vcc, s33, v51
	v_readlane_b32 s78, v252, 22
	v_readlane_b32 s79, v252, 23
	v_cndmask_b32_e32 v16, v51, v16, vcc
	v_rsq_f32_e32 v16, v16
	v_readlane_b32 s80, v252, 24
	v_readlane_b32 s81, v252, 25
	v_readlane_b32 s82, v252, 26
	v_mul_f32_e32 v51, 0x45800000, v16
	v_cndmask_b32_e32 v16, v16, v51, vcc
	v_pk_mul_f32 v[12:13], v[12:13], v[16:17] op_sel_hi:[1,0]
	v_pk_mul_f32 v[14:15], v[14:15], v[16:17] op_sel_hi:[1,0]
	v_cmp_gt_f32_e32 vcc, s33, v50
	v_readlane_b32 s83, v252, 27
	v_readlane_b32 s86, v252, 30
	v_readlane_b32 s87, v252, 31
	v_readlane_b32 s88, v252, 32
	v_readlane_b32 s89, v252, 33
	v_readlane_b32 s90, v252, 34
	v_readlane_b32 s91, v252, 35
	s_waitcnt vmcnt(0)
; __device__ __forceinline__ unsigned pk2(float lo, float hi) { return pg8::cvt_pk_bf16(lo, hi); }
; __device__ __forceinline__ float siluf(float x) { return x * __builtin_amdgcn_rcpf(1.0f + __expf(-x)); }
; template <int TY> __device__ __forceinline__ void mc_item(const Params& p, ldsp lds, int item) {
;     ...
;     for (int ei = 0; ei < ET; ++ei) { const int e0 = 16 * (wave * ET + ei) + 4 * q4; const f32x4 w4 = *(const f32x4*)(nwp + e0);
; #pragma unroll
;         for (int tk = 0; tk < 4; ++tk) { const size_t row = (size_t)row0 + 16 * tk + l15;
;             const u32x2 gw = *(const u32x2*)(Pb + row * PP + goff + e0);
;             const float g0 = bf2f(gw.x & 0xffffu), g1 = bf2f(gw.x >> 16), g2 = bf2f(gw.y & 0xffffu), g3 = bf2f(gw.y >> 16);
;             const f32x4 v = acc[ei][tk] * rstd[tk] * w4;
;             float y0 = v[0] * siluf(g0), y1 = v[1] * siluf(g1), y2 = v[2] * siluf(g2), y3 = v[3] * siluf(g3);
;     ...
;             if (!(fabsf(y0) < 1e30f)) y0 = 0.f; if (!(fabsf(y1) < 1e30f)) y1 = 0.f; if (!(fabsf(y2) < 1e30f)) y2 = 0.f; if (!(fabsf(y3) < 1e30f)) y3 = 0.f;
;     ...
;             u32x2 o; o.x = pk2(y0, y1); o.y = pk2(y2, y3);
;             *(u32x2*)(Y + row * LDY + ycol + e0) = o; } }
	v_lshlrev_b32_e32 v16, 16, v48
	v_mul_f32_e32 v52, 0xbfb8aa3b, v16
	v_exp_f32_e32 v52, v52
	v_and_b32_e32 v48, 0xffff0000, v48
	v_lshlrev_b32_e32 v51, 16, v49
	v_and_b32_e32 v49, 0xffff0000, v49
	v_mul_f32_e32 v53, 0xbfb8aa3b, v48
	v_mul_f32_e32 v54, 0xbfb8aa3b, v51
	v_mul_f32_e32 v55, 0xbfb8aa3b, v49
	v_exp_f32_e32 v53, v53
	v_add_f32_e32 v52, 1.0, v52
	v_exp_f32_e32 v54, v54
	v_exp_f32_e32 v55, v55
	v_rcp_f32_e32 v52, v52
	v_add_f32_e32 v53, 1.0, v53
	v_pk_mul_f32 v[12:13], v[12:13], v[18:19]
	v_add_f32_e32 v54, 1.0, v54
	v_rcp_f32_e32 v53, v53
	v_add_f32_e32 v55, 1.0, v55
	v_mul_f32_e32 v16, v52, v16
	v_rcp_f32_e32 v54, v54
	v_mul_f32_e32 v12, v12, v16
	v_rcp_f32_e32 v16, v55
	v_mul_f32_e32 v48, v53, v48
	v_pk_mul_f32 v[14:15], v[14:15], v[20:21]
	v_mul_f32_e32 v13, v13, v48
	v_mul_f32_e32 v48, v54, v51
	v_mul_f32_e32 v16, v16, v49
	v_mul_f32_e32 v14, v14, v48
	v_mul_f32_e32 v15, v15, v16
	v_cvt_pk_bf16_f32 v12, v12, v13
	v_cvt_pk_bf16_f32 v13, v14, v15
	v_lshlrev_b64 v[14:15], 11, v[22:23]
	v_lshl_add_u64 v[14:15], v[24:25], 0, v[14:15]
	global_store_dwordx2 v[14:15], v[12:13], off nt
	v_or_b32_e32 v12, 16, v22
	v_mad_i64_i32 v[14:15], s[0:1], v12, s55, v[28:29]
	v_lshl_add_u64 v[14:15], v[14:15], 0, v[26:27]
	v_mul_f32_e32 v16, 0x4b800000, v50
	v_cndmask_b32_e32 v16, v50, v16, vcc
	v_rsq_f32_e32 v16, v16
	v_mov_b32_e32 v13, s13
	v_or_b32_e32 v48, 32, v22
	v_lshlrev_b64 v[12:13], 11, v[12:13]
	v_mul_f32_e32 v49, 0x45800000, v16
	v_cndmask_b32_e32 v16, v16, v49, vcc
	v_pk_mul_f32 v[8:9], v[8:9], v[16:17] op_sel_hi:[1,0]
	v_pk_mul_f32 v[10:11], v[10:11], v[16:17] op_sel_hi:[1,0]
	v_pk_mul_f32 v[8:9], v[8:9], v[18:19]
	v_mad_i64_i32 v[50:51], s[0:1], v48, s55, v[28:29]
	v_lshl_add_u64 v[12:13], v[24:25], 0, v[12:13]
	v_pk_mul_f32 v[10:11], v[10:11], v[20:21]
	v_lshl_add_u64 v[50:51], v[50:51], 0, v[26:27]
	v_or_b32_e32 v22, 48, v22
	v_lshlrev_b32_e32 v16, 16, v144
	v_and_b32_e32 v14, 0xffff0000, v144
	v_lshlrev_b32_e32 v49, 16, v145
	v_and_b32_e32 v15, 0xffff0000, v145
	v_mul_f32_e32 v52, 0xbfb8aa3b, v16
	v_mul_f32_e32 v53, 0xbfb8aa3b, v14
	v_mul_f32_e32 v54, 0xbfb8aa3b, v49
	v_mul_f32_e32 v55, 0xbfb8aa3b, v15
	v_exp_f32_e32 v52, v52
	v_exp_f32_e32 v53, v53
	v_exp_f32_e32 v54, v54
	v_exp_f32_e32 v55, v55
	v_add_f32_e32 v52, 1.0, v52
	v_add_f32_e32 v53, 1.0, v53
	v_add_f32_e32 v54, 1.0, v54
	v_add_f32_e32 v55, 1.0, v55
	v_rcp_f32_e32 v52, v52
	v_rcp_f32_e32 v53, v53
	v_rcp_f32_e32 v54, v54
	v_rcp_f32_e32 v55, v55
	v_mul_f32_e32 v16, v52, v16
	v_mul_f32_e32 v14, v53, v14
	v_mul_f32_e32 v49, v54, v49
	v_mul_f32_e32 v15, v55, v15
	v_mul_f32_e32 v8, v8, v16
	v_mul_f32_e32 v9, v9, v14
	v_mul_f32_e32 v10, v10, v49
	v_mul_f32_e32 v11, v11, v15
	v_cvt_pk_bf16_f32 v8, v8, v9
	v_cvt_pk_bf16_f32 v9, v10, v11
	global_store_dwordx2 v[12:13], v[8:9], off nt
	s_waitcnt lgkmcnt(7)
	v_mov_b32_e32 v12, v47
	v_mov_b32_e32 v13, v46
	s_waitcnt lgkmcnt(6)
	v_mov_b32_e32 v14, v45
	v_mov_b32_e32 v15, v44
	v_pk_add_f32 v[12:13], v[12:13], 0 op_sel_hi:[1,0]
	s_waitcnt lgkmcnt(5)
	v_mov_b32_e32 v44, v43
	v_mov_b32_e32 v45, v42
	v_pk_add_f32 v[12:13], v[12:13], v[14:15]
	s_waitcnt lgkmcnt(4)
	v_mov_b32_e32 v42, v41
	v_mov_b32_e32 v43, v40
	v_pk_add_f32 v[12:13], v[12:13], v[44:45]
	s_waitcnt lgkmcnt(3)
	v_mov_b32_e32 v40, v39
	v_mov_b32_e32 v41, v38
	v_pk_add_f32 v[12:13], v[12:13], v[42:43]
	s_waitcnt lgkmcnt(2)
	v_mov_b32_e32 v38, v37
	v_mov_b32_e32 v39, v36
	v_pk_add_f32 v[12:13], v[12:13], v[40:41]
	s_waitcnt lgkmcnt(1)
	v_mov_b32_e32 v36, v35
	v_mov_b32_e32 v37, v34
	v_pk_add_f32 v[12:13], v[12:13], v[38:39]
	s_waitcnt lgkmcnt(0)
	v_mov_b32_e32 v34, v33
	v_mov_b32_e32 v35, v32
	v_pk_add_f32 v[12:13], v[12:13], v[36:37]
	v_mov_b32_e32 v49, s13
	v_pk_add_f32 v[12:13], v[12:13], v[34:35]
	v_lshlrev_b64 v[10:11], 11, v[48:49]
	v_pk_fma_f32 v[12:13], v[12:13], s[10:11], v[30:31] op_sel_hi:[1,0,0]
	v_lshl_add_u64 v[10:11], v[24:25], 0, v[10:11]
	v_mul_f32_e32 v14, 0x4b800000, v13
	v_cmp_gt_f32_e32 vcc, s33, v13
	s_nop 1
	v_cndmask_b32_e32 v13, v13, v14, vcc
	v_rsq_f32_e32 v13, v13
	v_mad_i64_i32 v[14:15], s[0:1], v22, s55, v[28:29]
	v_lshl_add_u64 v[14:15], v[14:15], 0, v[26:27]
	v_mul_f32_e32 v16, 0x45800000, v13
	v_cndmask_b32_e32 v16, v13, v16, vcc
	v_pk_mul_f32 v[4:5], v[4:5], v[16:17] op_sel_hi:[1,0]
	v_pk_mul_f32 v[6:7], v[6:7], v[16:17] op_sel_hi:[1,0]
	v_pk_mul_f32 v[4:5], v[18:19], v[4:5]
	v_pk_mul_f32 v[6:7], v[20:21], v[6:7]
	v_cmp_gt_f32_e32 vcc, s33, v12
	v_lshlrev_b32_e32 v13, 16, v154
	v_and_b32_e32 v8, 0xffff0000, v154
	v_lshlrev_b32_e32 v16, 16, v155
	v_and_b32_e32 v9, 0xffff0000, v155
	v_mul_f32_e32 v26, 0xbfb8aa3b, v13
	v_mul_f32_e32 v27, 0xbfb8aa3b, v8
	v_mul_f32_e32 v28, 0xbfb8aa3b, v16
	v_mul_f32_e32 v29, 0xbfb8aa3b, v9
	v_exp_f32_e32 v26, v26
	v_exp_f32_e32 v27, v27
	v_exp_f32_e32 v28, v28
	v_exp_f32_e32 v29, v29
	v_add_f32_e32 v26, 1.0, v26
	v_add_f32_e32 v27, 1.0, v27
	v_add_f32_e32 v28, 1.0, v28
	v_add_f32_e32 v29, 1.0, v29
	v_rcp_f32_e32 v26, v26
	v_rcp_f32_e32 v27, v27
	v_rcp_f32_e32 v28, v28
	v_rcp_f32_e32 v29, v29
	v_mul_f32_e32 v13, v26, v13
	v_mul_f32_e32 v8, v27, v8
	v_mul_f32_e32 v16, v28, v16
	v_mul_f32_e32 v9, v29, v9
	v_mul_f32_e32 v4, v4, v13
	v_mul_f32_e32 v5, v5, v8
	v_mul_f32_e32 v6, v6, v16
	v_mul_f32_e32 v7, v7, v9
	v_cvt_pk_bf16_f32 v4, v4, v5
	v_cvt_pk_bf16_f32 v5, v6, v7
	global_store_dwordx2 v[10:11], v[4:5], off nt
	v_mul_f32_e32 v6, 0x4b800000, v12
	v_cndmask_b32_e32 v6, v12, v6, vcc
	v_rsq_f32_e32 v8, v6
	v_lshlrev_b64 v[6:7], 11, v[22:23]
	v_mul_f32_e32 v9, 0x45800000, v8
	v_cndmask_b32_e32 v8, v8, v9, vcc
	v_pk_mul_f32 v[0:1], v[0:1], v[8:9] op_sel_hi:[1,0]
	v_pk_mul_f32 v[2:3], v[2:3], v[8:9] op_sel_hi:[1,0]
	v_pk_mul_f32 v[0:1], v[18:19], v[0:1]
	v_pk_mul_f32 v[2:3], v[20:21], v[2:3]
	v_lshlrev_b32_e32 v8, 16, v168
	v_and_b32_e32 v4, 0xffff0000, v168
	v_lshlrev_b32_e32 v9, 16, v169
	v_and_b32_e32 v5, 0xffff0000, v169
	v_mul_f32_e32 v10, 0xbfb8aa3b, v8
	v_mul_f32_e32 v11, 0xbfb8aa3b, v4
	v_mul_f32_e32 v12, 0xbfb8aa3b, v9
	v_mul_f32_e32 v13, 0xbfb8aa3b, v5
	v_exp_f32_e32 v10, v10
	v_exp_f32_e32 v11, v11
	v_exp_f32_e32 v12, v12
	v_exp_f32_e32 v13, v13
	v_add_f32_e32 v10, 1.0, v10
	v_add_f32_e32 v11, 1.0, v11
	v_add_f32_e32 v12, 1.0, v12
	v_add_f32_e32 v13, 1.0, v13
	v_rcp_f32_e32 v10, v10
	v_rcp_f32_e32 v11, v11
	v_rcp_f32_e32 v12, v12
	v_rcp_f32_e32 v13, v13
	v_mul_f32_e32 v8, v10, v8
	v_mul_f32_e32 v4, v11, v4
	v_mul_f32_e32 v9, v12, v9
	v_mul_f32_e32 v5, v13, v5
	v_mul_f32_e32 v0, v0, v8
	v_mul_f32_e32 v1, v1, v4
	v_mul_f32_e32 v2, v2, v9
	v_mul_f32_e32 v3, v3, v5
	v_cvt_pk_bf16_f32 v0, v0, v1
	v_cvt_pk_bf16_f32 v1, v2, v3
	v_lshl_add_u64 v[2:3], v[24:25], 0, v[6:7]
	global_store_dwordx2 v[2:3], v[0:1], off nt
	s_waitcnt vmcnt(0) lgkmcnt(0)
	s_barrier

; __device__ __forceinline__ float siluf(float x) { return x * __builtin_amdgcn_rcpf(1.0f + __expf(-x)); }
; #define BSYNC() do { asm volatile("s_waitcnt vmcnt(0) lgkmcnt(0)" ::: "memory"); __syncthreads(); } while (0)
; template <int TY> __device__ __forceinline__ void mc_item(const Params& p, ldsp lds, int item) {
;     ...
;     BSYNC();
; #pragma unroll
;     for (int tk = 0; tk < 4; ++tk) { float s = 0.f;
; #pragma unroll
;         for (int w = 0; w < 8; ++w) s += RED[w * 64 + 16 * tk + l15];
;         rstd[tk] = rsqrtf(s * (1.0f / DV) + EPS); }
;     const float* nwp = TY == 0 ? p.in[12] : (TY == 1 ? p.in[14] : p.in[17]);
;     const int goff = TY == 0 ? E_RA + h * 128 : (TY == 1 ? E_GB + h * 128 : O_G + h * 512);
;     constexpr int LDY = TY == 2 ? 2048 : 1024; const int ycol = TY == 0 ? h * 128 : (TY == 1 ? 512 + h * 128 : h * 512);
;     bf16_t* Y = (bf16_t*)(p.ws + WS_Y);
; #pragma unroll
;     for (int ei = 0; ei < ET; ++ei) { const int e0 = 16 * (wave * ET + ei) + 4 * q4; const f32x4 w4 = *(const f32x4*)(nwp + e0);
; #pragma unroll
;         for (int tk = 0; tk < 4; ++tk) { const size_t row = (size_t)row0 + 16 * tk + l15;
;             const u32x2 gw = *(const u32x2*)(Pb + row * PP + goff + e0);
;             const float g0 = bf2f(gw.x & 0xffffu), g1 = bf2f(gw.x >> 16), g2 = bf2f(gw.y & 0xffffu), g3 = bf2f(gw.y >> 16);
;             const f32x4 v = acc[ei][tk] * rstd[tk] * w4;
;             float y0 = v[0] * siluf(g0), y1 = v[1] * siluf(g1), y2 = v[2] * siluf(g2), y3 = v[3] * siluf(g3);
.LBB0_1281:
	s_or_b64 exec, exec, s[0:1]
	v_lshl_add_u32 v8, v23, 2, 0
	v_add_u32_e32 v16, 0x13800, v8
	s_waitcnt vmcnt(0) lgkmcnt(0)
	s_waitcnt lgkmcnt(0)
	s_barrier
	ds_read2_b32 v[8:9], v16 offset1:16
	ds_read2_b32 v[10:11], v16 offset0:64 offset1:80
	ds_read2_b32 v[26:27], v16 offset0:128 offset1:144
	ds_read2_b32 v[28:29], v16 offset0:192 offset1:208
	v_add_u32_e32 v22, 0x400, v16
	s_waitcnt lgkmcnt(3)
	v_mov_b32_e32 v38, v9
	v_mov_b32_e32 v39, v8
	v_pk_add_f32 v[8:9], v[38:39], 0 op_sel_hi:[1,0]
	s_waitcnt lgkmcnt(2)
	v_mov_b32_e32 v38, v11
	v_mov_b32_e32 v39, v10
	ds_read2_b32 v[30:31], v22 offset1:16
	ds_read2_b32 v[32:33], v22 offset0:64 offset1:80
	ds_read2_b32 v[34:35], v22 offset0:128 offset1:144
	ds_read2_b32 v[36:37], v22 offset0:192 offset1:208
	v_pk_add_f32 v[8:9], v[8:9], v[38:39]
	s_waitcnt lgkmcnt(5)
	v_mov_b32_e32 v10, v27
	v_mov_b32_e32 v11, v26
	v_pk_add_f32 v[8:9], v[8:9], v[10:11]
	s_waitcnt lgkmcnt(4)
	v_mov_b32_e32 v10, v29
	v_mov_b32_e32 v11, v28
	v_pk_add_f32 v[8:9], v[8:9], v[10:11]
	s_waitcnt lgkmcnt(3)
	v_mov_b32_e32 v10, v31
	v_mov_b32_e32 v11, v30
	v_pk_add_f32 v[8:9], v[8:9], v[10:11]
	s_waitcnt lgkmcnt(2)
	v_mov_b32_e32 v10, v33
	v_mov_b32_e32 v11, v32
	v_pk_add_f32 v[8:9], v[8:9], v[10:11]
	s_waitcnt lgkmcnt(1)
	v_mov_b32_e32 v10, v35
	v_mov_b32_e32 v11, v34
	v_pk_add_f32 v[8:9], v[8:9], v[10:11]
	s_waitcnt lgkmcnt(0)
	v_mov_b32_e32 v10, v37
	v_mov_b32_e32 v11, v36
	s_mov_b32 s0, 0x358637bd
	v_pk_add_f32 v[8:9], v[8:9], v[10:11]
	v_mov_b64_e32 v[10:11], s[0:1]
	s_brev_b32 s12, 60
	v_pk_fma_f32 v[8:9], v[8:9], s[12:13], v[10:11] op_sel_hi:[1,0,0]
	v_or_b32_e32 v24, s11, v24
	v_mul_f32_e32 v25, 0x4b800000, v9
	v_cmp_gt_f32_e64 s[0:1], s33, v9
	v_cmp_gt_f32_e32 vcc, s33, v8
	v_readlane_b32 s76, v252, 20
	v_cndmask_b32_e64 v9, v9, v25, s[0:1]
	v_rsq_f32_e32 v9, v9
	v_readlane_b32 s88, v252, 32
	v_readlane_b32 s89, v252, 33
	v_readlane_b32 s77, v252, 21
	v_mul_f32_e32 v25, 0x45800000, v9
	v_cndmask_b32_e64 v32, v9, v25, s[0:1]
	v_mul_f32_e32 v9, 0x4b800000, v8
	v_cndmask_b32_e32 v8, v8, v9, vcc
	v_rsq_f32_e32 v8, v8
	v_ashrrev_i32_e32 v25, 31, v24
	v_readlane_b32 s78, v252, 22
	v_readlane_b32 s79, v252, 23
	v_mul_f32_e32 v9, 0x45800000, v8
	v_cndmask_b32_e32 v30, v8, v9, vcc
	ds_read2_b32 v[8:9], v16 offset0:32 offset1:48
	ds_read2_b32 v[26:27], v16 offset0:96 offset1:112
	ds_read2_b32 v[28:29], v16 offset0:160 offset1:176
	ds_read2_b32 v[34:35], v16 offset0:224 offset1:240
	ds_read2_b32 v[36:37], v22 offset0:32 offset1:48
	ds_read2_b32 v[38:39], v22 offset0:96 offset1:112
	ds_read2_b32 v[40:41], v22 offset0:160 offset1:176
	ds_read2_b32 v[42:43], v22 offset0:224 offset1:240
	s_waitcnt lgkmcnt(7)
	v_mov_b32_e32 v44, v9
	v_mov_b32_e32 v45, v8
	v_pk_add_f32 v[8:9], v[44:45], 0 op_sel_hi:[1,0]
	s_waitcnt lgkmcnt(6)
	v_mov_b32_e32 v44, v27
	v_mov_b32_e32 v45, v26
	v_pk_add_f32 v[8:9], v[8:9], v[44:45]
	s_waitcnt lgkmcnt(5)
	v_mov_b32_e32 v26, v29
	v_mov_b32_e32 v27, v28
	v_pk_add_f32 v[8:9], v[8:9], v[26:27]
	s_waitcnt lgkmcnt(4)
	v_mov_b32_e32 v26, v35
	v_mov_b32_e32 v27, v34
	v_pk_add_f32 v[8:9], v[8:9], v[26:27]
	s_waitcnt lgkmcnt(3)
	v_mov_b32_e32 v26, v37
	v_mov_b32_e32 v27, v36
	v_pk_add_f32 v[8:9], v[8:9], v[26:27]
	s_waitcnt lgkmcnt(2)
	v_mov_b32_e32 v26, v39
	v_mov_b32_e32 v27, v38
	v_pk_add_f32 v[8:9], v[8:9], v[26:27]
	s_waitcnt lgkmcnt(1)
	v_mov_b32_e32 v26, v41
	v_mov_b32_e32 v27, v40
	v_pk_add_f32 v[8:9], v[8:9], v[26:27]
	s_waitcnt lgkmcnt(0)
	v_mov_b32_e32 v26, v43
	v_mov_b32_e32 v27, v42
	v_pk_add_f32 v[8:9], v[8:9], v[26:27]
	v_or_b32_e32 v16, s9, v23
	v_pk_fma_f32 v[8:9], v[8:9], s[12:13], v[10:11] op_sel_hi:[1,0,0]
	s_add_u32 s12, s26, s10
	v_mul_f32_e32 v10, 0x4b800000, v9
	v_cmp_gt_f32_e64 s[0:1], s33, v9
	v_cmp_gt_f32_e32 vcc, s33, v8
	s_addc_u32 s13, s27, 0
	v_cndmask_b32_e64 v9, v9, v10, s[0:1]
	v_rsq_f32_e32 v9, v9
	v_mov_b64_e32 v[28:29], s[12:13]
	s_mov_b32 s9, 0x1ec21000
	v_readlane_b32 s80, v252, 24
	v_mul_f32_e32 v10, 0x45800000, v9
	v_cndmask_b32_e64 v26, v9, v10, s[0:1]
	v_mul_f32_e32 v9, 0x4b800000, v8
	v_cndmask_b32_e32 v8, v8, v9, vcc
	v_rsq_f32_e32 v8, v8
	s_add_u32 s0, s68, s10
	v_mad_u64_u32 v[34:35], s[10:11], v16, s55, v[28:29]
	v_mul_f32_e32 v9, 0x45800000, v8
	v_cndmask_b32_e32 v22, v8, v9, vcc
	v_lshl_add_u64 v[8:9], v[24:25], 2, s[88:89]
	v_lshlrev_b64 v[24:25], 1, v[24:25]
	v_lshl_add_u64 v[34:35], v[34:35], 0, v[24:25]
	v_add_co_u32_e32 v34, vcc, s57, v34
	global_load_dwordx4 v[8:11], v[8:9], off
	s_nop 0
	v_addc_co_u32_e32 v35, vcc, 0, v35, vcc
	global_load_dwordx2 v[34:35], v[34:35], off offset:2048 nt
	s_mov_b32 s98, s57
	s_mov_b32 s99, 0
	v_or_b32_e32 v64, 16, v16
	v_mad_u64_u32 v[134:135], s[10:11], v64, s55, v[28:29]
	v_lshl_add_u64 v[140:141], v[134:135], 0, v[24:25]
	v_lshl_add_u64 v[142:143], v[140:141], 0, s[98:99]
	global_load_dwordx2 v[144:145], v[142:143], off offset:2048 nt
	v_or_b32_e32 v146, 32, v16
	v_mad_u64_u32 v[148:149], s[10:11], v146, s55, v[28:29]
	v_lshl_add_u64 v[150:151], v[148:149], 0, v[24:25]
	v_lshl_add_u64 v[152:153], v[150:151], 0, s[98:99]
	global_load_dwordx2 v[154:155], v[152:153], off offset:2048 nt
	v_or_b32_e32 v156, 48, v16
	v_mad_u64_u32 v[166:167], s[10:11], v156, s55, v[28:29]
	v_lshl_add_u64 v[168:169], v[166:167], 0, v[24:25]
	v_lshl_add_u64 v[172:173], v[168:169], 0, s[98:99]
	global_load_dwordx2 v[174:175], v[172:173], off offset:2048 nt
	s_addc_u32 s1, s69, 0
	v_readlane_b32 s81, v252, 25
	v_readlane_b32 s82, v252, 26
	v_readlane_b32 s83, v252, 27
	v_readlane_b32 s84, v252, 28
	v_readlane_b32 s85, v252, 29
	v_readlane_b32 s86, v252, 30
	v_readlane_b32 s87, v252, 31
	v_readlane_b32 s90, v252, 34
	v_readlane_b32 s91, v252, 35
	s_waitcnt vmcnt(0)
; __device__ __forceinline__ unsigned pk2(float lo, float hi) { return pg8::cvt_pk_bf16(lo, hi); }
; __device__ __forceinline__ float siluf(float x) { return x * __builtin_amdgcn_rcpf(1.0f + __expf(-x)); }
; template <int TY> __device__ __forceinline__ void mc_item(const Params& p, ldsp lds, int item) {
;     ...
;     for (int ei = 0; ei < ET; ++ei) { const int e0 = 16 * (wave * ET + ei) + 4 * q4; const f32x4 w4 = *(const f32x4*)(nwp + e0);
; #pragma unroll
;         for (int tk = 0; tk < 4; ++tk) { const size_t row = (size_t)row0 + 16 * tk + l15;
;             const u32x2 gw = *(const u32x2*)(Pb + row * PP + goff + e0);
;             const float g0 = bf2f(gw.x & 0xffffu), g1 = bf2f(gw.x >> 16), g2 = bf2f(gw.y & 0xffffu), g3 = bf2f(gw.y >> 16);
;             const f32x4 v = acc[ei][tk] * rstd[tk] * w4;
;             float y0 = v[0] * siluf(g0), y1 = v[1] * siluf(g1), y2 = v[2] * siluf(g2), y3 = v[3] * siluf(g3);
;     ...
;             if (!(fabsf(y0) < 1e30f)) y0 = 0.f; if (!(fabsf(y1) < 1e30f)) y1 = 0.f; if (!(fabsf(y2) < 1e30f)) y2 = 0.f; if (!(fabsf(y3) < 1e30f)) y3 = 0.f;
;     ...
;             u32x2 o; o.x = pk2(y0, y1); o.y = pk2(y2, y3);
;             *(u32x2*)(Y + row * LDY + ycol + e0) = o; } }
	v_lshlrev_b32_e32 v23, 16, v34
	v_and_b32_e32 v33, 0xffff0000, v35
	v_pk_mul_f32 v[18:19], v[18:19], v[32:33] op_sel_hi:[1,0]
	v_pk_mul_f32 v[20:21], v[20:21], v[32:33] op_sel_hi:[1,0]
	v_mul_f32_e32 v32, 0xbfb8aa3b, v23
	v_exp_f32_e32 v32, v32
	v_and_b32_e32 v27, 0xffff0000, v34
	v_pk_mul_f32 v[18:19], v[18:19], v[8:9]
	v_lshlrev_b32_e32 v31, 16, v35
	v_add_f32_e32 v32, 1.0, v32
	v_rcp_f32_e32 v32, v32
	v_pk_mul_f32 v[20:21], v[20:21], v[10:11]
	v_pk_mul_f32 v[12:13], v[12:13], v[30:31] op_sel_hi:[1,0]
	v_pk_mul_f32 v[14:15], v[14:15], v[30:31] op_sel_hi:[1,0]
	v_mul_f32_e32 v23, v32, v23
	v_mul_f32_e32 v18, v18, v23
	v_mul_f32_e32 v23, 0xbfb8aa3b, v27
	v_exp_f32_e32 v23, v23
	v_pk_mul_f32 v[12:13], v[12:13], v[8:9]
	v_pk_mul_f32 v[14:15], v[14:15], v[10:11]
	v_add_f32_e32 v23, 1.0, v23
	v_rcp_f32_e32 v23, v23
	s_nop 0
	v_mul_f32_e32 v23, v23, v27
	v_mul_f32_e32 v19, v19, v23
	v_mul_f32_e32 v23, 0xbfb8aa3b, v31
	v_exp_f32_e32 v23, v23
	v_cvt_pk_bf16_f32 v18, v18, v19
	s_nop 0
	v_add_f32_e32 v23, 1.0, v23
	v_rcp_f32_e32 v23, v23
	s_nop 0
	v_mul_f32_e32 v23, v23, v31
	v_mul_f32_e32 v20, v20, v23
	v_mul_f32_e32 v23, 0xbfb8aa3b, v33
	v_exp_f32_e32 v23, v23
	s_nop 0
	v_add_f32_e32 v23, 1.0, v23
	v_rcp_f32_e32 v23, v23
	s_nop 0
	v_mul_f32_e32 v23, v23, v33
	v_mul_f32_e32 v21, v21, v23
	v_cvt_pk_bf16_f32 v19, v20, v21
	v_lshlrev_b64 v[20:21], 11, v[16:17]
	v_lshl_add_u64 v[20:21], s[0:1], 0, v[20:21]
	v_lshl_add_u64 v[20:21], v[20:21], 0, v[24:25]
	v_add_co_u32_e32 v20, vcc, s9, v20
	s_nop 1
	v_addc_co_u32_e32 v21, vcc, 0, v21, vcc
	global_store_dwordx2 v[20:21], v[18:19], off offset:1024 nt
	v_or_b32_e32 v18, 16, v16
	v_mad_u64_u32 v[20:21], s[10:11], v18, s55, v[28:29]
	v_lshl_add_u64 v[20:21], v[20:21], 0, v[24:25]
	s_nop 0
	v_mov_b32_e32 v19, v17
	s_nop 0
	v_lshl_add_u64 v[20:21], v[20:21], 0, s[98:99]
	v_lshlrev_b32_e32 v23, 16, v144
	v_mul_f32_e32 v30, 0xbfb8aa3b, v23
	v_exp_f32_e32 v30, v30
	v_and_b32_e32 v20, 0xffff0000, v144
	v_lshlrev_b32_e32 v27, 16, v145
	v_and_b32_e32 v21, 0xffff0000, v145
	v_add_f32_e32 v30, 1.0, v30
	v_rcp_f32_e32 v30, v30
	v_pk_mul_f32 v[4:5], v[4:5], v[26:27] op_sel_hi:[1,0]
	v_pk_mul_f32 v[6:7], v[6:7], v[26:27] op_sel_hi:[1,0]
	v_pk_mul_f32 v[4:5], v[8:9], v[4:5]
	v_mul_f32_e32 v23, v30, v23
	v_mul_f32_e32 v12, v12, v23
	v_mul_f32_e32 v23, 0xbfb8aa3b, v20
	v_exp_f32_e32 v23, v23
	v_pk_mul_f32 v[6:7], v[10:11], v[6:7]
	v_add_f32_e32 v23, 1.0, v23
	v_rcp_f32_e32 v23, v23
	s_nop 0
	v_mul_f32_e32 v20, v23, v20
	v_mul_f32_e32 v13, v13, v20
	v_mul_f32_e32 v20, 0xbfb8aa3b, v27
	v_exp_f32_e32 v20, v20
	v_cvt_pk_bf16_f32 v12, v12, v13
	v_pk_mul_f32 v[0:1], v[0:1], v[22:23] op_sel_hi:[1,0]
	v_pk_mul_f32 v[2:3], v[2:3], v[22:23] op_sel_hi:[1,0]
	v_add_f32_e32 v20, 1.0, v20
	v_rcp_f32_e32 v20, v20
	v_pk_mul_f32 v[0:1], v[8:9], v[0:1]
	v_pk_mul_f32 v[2:3], v[10:11], v[2:3]
	v_mul_f32_e32 v20, v20, v27
	v_mul_f32_e32 v14, v14, v20
	v_mul_f32_e32 v20, 0xbfb8aa3b, v21
	v_exp_f32_e32 v20, v20
	s_nop 0
	v_add_f32_e32 v20, 1.0, v20
	v_rcp_f32_e32 v20, v20
	s_nop 0
	v_mul_f32_e32 v20, v20, v21
	v_mul_f32_e32 v15, v15, v20
	v_cvt_pk_bf16_f32 v13, v14, v15
	v_lshlrev_b64 v[14:15], 11, v[18:19]
	v_lshl_add_u64 v[14:15], s[0:1], 0, v[14:15]
	v_lshl_add_u64 v[14:15], v[14:15], 0, v[24:25]
	v_add_co_u32_e32 v14, vcc, s9, v14
	s_nop 1
	v_addc_co_u32_e32 v15, vcc, 0, v15, vcc
	global_store_dwordx2 v[14:15], v[12:13], off offset:1024 nt
	v_or_b32_e32 v12, 32, v16
	v_mad_u64_u32 v[14:15], s[10:11], v12, s55, v[28:29]
	v_lshl_add_u64 v[14:15], v[14:15], 0, v[24:25]
	s_nop 0
	v_mov_b32_e32 v13, v17
	s_nop 0
	v_lshl_add_u64 v[14:15], v[14:15], 0, s[98:99]
	v_or_b32_e32 v16, 48, v16
	v_lshlrev_b32_e32 v18, 16, v154
	v_mul_f32_e32 v20, 0xbfb8aa3b, v18
	v_exp_f32_e32 v20, v20
	v_and_b32_e32 v14, 0xffff0000, v154
	v_lshlrev_b32_e32 v19, 16, v155
	v_and_b32_e32 v15, 0xffff0000, v155
	v_add_f32_e32 v20, 1.0, v20
	v_rcp_f32_e32 v20, v20
	s_nop 0
	v_mul_f32_e32 v18, v20, v18
	v_mul_f32_e32 v4, v4, v18
	v_mul_f32_e32 v18, 0xbfb8aa3b, v14
	v_exp_f32_e32 v18, v18
	s_nop 0
	v_add_f32_e32 v18, 1.0, v18
	v_rcp_f32_e32 v18, v18
	s_nop 0
	v_mul_f32_e32 v14, v18, v14
	v_mul_f32_e32 v5, v5, v14
	v_mul_f32_e32 v14, 0xbfb8aa3b, v19
	v_exp_f32_e32 v14, v14
	v_cvt_pk_bf16_f32 v4, v4, v5
	s_nop 0
	v_add_f32_e32 v14, 1.0, v14
	v_rcp_f32_e32 v14, v14
	s_nop 0
	v_mul_f32_e32 v14, v14, v19
	v_mul_f32_e32 v6, v6, v14
	v_mul_f32_e32 v14, 0xbfb8aa3b, v15
	v_exp_f32_e32 v14, v14
	s_nop 0
	v_add_f32_e32 v14, 1.0, v14
	v_rcp_f32_e32 v14, v14
	s_nop 0
	v_mul_f32_e32 v14, v14, v15
	v_mul_f32_e32 v7, v7, v14
	v_cvt_pk_bf16_f32 v5, v6, v7
	v_lshlrev_b64 v[6:7], 11, v[12:13]
	v_lshl_add_u64 v[6:7], s[0:1], 0, v[6:7]
	v_lshl_add_u64 v[6:7], v[6:7], 0, v[24:25]
	v_add_co_u32_e32 v6, vcc, s9, v6
	s_nop 1
	v_addc_co_u32_e32 v7, vcc, 0, v7, vcc
	global_store_dwordx2 v[6:7], v[4:5], off offset:1024 nt
	v_mad_u64_u32 v[4:5], s[10:11], v16, s55, v[28:29]
	v_lshl_add_u64 v[4:5], v[4:5], 0, v[24:25]
	s_nop 0
	s_nop 1
	v_lshl_add_u64 v[4:5], v[4:5], 0, s[98:99]
	v_lshlrev_b32_e32 v6, 16, v174
	v_mul_f32_e32 v8, 0xbfb8aa3b, v6
	v_exp_f32_e32 v8, v8
	v_and_b32_e32 v4, 0xffff0000, v174
	v_lshlrev_b32_e32 v7, 16, v175
	v_and_b32_e32 v5, 0xffff0000, v175
	v_add_f32_e32 v8, 1.0, v8
	v_rcp_f32_e32 v8, v8
	s_nop 0
	v_mul_f32_e32 v6, v8, v6
	v_mul_f32_e32 v0, v0, v6
	v_mul_f32_e32 v6, 0xbfb8aa3b, v4
	v_exp_f32_e32 v6, v6
	s_nop 0
	v_add_f32_e32 v6, 1.0, v6
	v_rcp_f32_e32 v6, v6
	s_nop 0
	v_mul_f32_e32 v4, v6, v4
	v_mul_f32_e32 v1, v1, v4
	v_mul_f32_e32 v4, 0xbfb8aa3b, v7
	v_exp_f32_e32 v4, v4
	v_cvt_pk_bf16_f32 v0, v0, v1
	s_nop 0
	v_add_f32_e32 v4, 1.0, v4
	v_rcp_f32_e32 v4, v4
	s_nop 0
	v_mul_f32_e32 v4, v4, v7
	v_mul_f32_e32 v2, v2, v4
	v_mul_f32_e32 v4, 0xbfb8aa3b, v5
	v_exp_f32_e32 v4, v4
	s_nop 0
	v_add_f32_e32 v4, 1.0, v4
	v_rcp_f32_e32 v4, v4
	s_nop 0
	v_mul_f32_e32 v4, v4, v5
	v_mul_f32_e32 v3, v3, v4
	v_cvt_pk_bf16_f32 v1, v2, v3
	v_lshlrev_b64 v[2:3], 11, v[16:17]
	v_lshl_add_u64 v[2:3], s[0:1], 0, v[2:3]
	v_lshl_add_u64 v[2:3], v[2:3], 0, v[24:25]
	v_add_co_u32_e32 v2, vcc, 0x1ec21000, v2
	s_nop 1
	v_addc_co_u32_e32 v3, vcc, 0, v3, vcc
	global_store_dwordx2 v[2:3], v[0:1], off offset:1024 nt
	s_waitcnt vmcnt(0) lgkmcnt(0)
	s_barrier
	s_branch .LBB0_1267
